# GEMM K-loops (MLP-up, out-proj/MLP-down, in-proj): first iteration peeled with srcC=0 instead of 128 v_mov accumulator zeroing; plus weight-copy in in-proj tails
# speedup vs baseline: 1.0570x; 1.0066x over previous
.LBB0_849:
	s_ashr_i32 s19, s18, 31
	s_lshl_b64 s[20:21], s[18:19], 19
	s_add_u32 s42, s88, s20
	s_addc_u32 s43, s89, s21
	s_and_b64 s[20:21], s[40:41], exec
	s_cselect_b32 s19, s43, s53
	s_cselect_b32 s47, s42, s52
	s_ashr_i32 s17, s16, 31
	s_lshl_b64 s[20:21], s[16:17], 19
	s_add_u32 s44, s24, s20
	s_addc_u32 s45, s25, s21
	s_and_b64 s[20:21], s[40:41], exec
	s_cselect_b32 s17, s45, s51
	s_cselect_b32 s63, s44, s50
	s_add_u32 s64, s50, 0x100
	s_addc_u32 s65, s51, 0
	s_add_u32 s50, s52, 0x40080
	s_addc_u32 s51, s53, 0
	s_mov_b32 s66, -2
	s_add_u32 s20, s50, 0xfffc0080
	s_addc_u32 s21, s51, -1
	s_add_i32 s23, 0, 0x10000
	s_cmp_eq_u32 s66, 12
	s_cselect_b32 s55, s19, s21
	s_cselect_b32 s54, s47, s20
	v_add_u32_e32 v98, s23, v175
	s_cselect_b32 s53, s17, s65
	s_cselect_b32 s52, s63, s64
	s_add_i32 s67, 0, 0x14000
	ds_read_b128 v[108:111], v98
	ds_read_b128 v[112:115], v98 offset:1024
	ds_read_b128 v[120:123], v98 offset:2048
	ds_read_b128 v[128:131], v98 offset:3072
	v_add_u32_e32 v98, s67, v175
	ds_read_b128 v[158:161], v98
	ds_read_b128 v[162:165], v98 offset:1024
	ds_read_b128 v[166:169], v98 offset:2048
	ds_read_b128 v[170:173], v98 offset:3072
	v_lshl_add_u64 v[178:179], s[50:51], 0, v[156:157]
	s_add_i32 m0, s37, 0xc000
	ds_read_b128 v[188:191], v177
	ds_read_b128 v[192:195], v177 offset:1024
	ds_read_b128 v[196:199], v177 offset:2048
	ds_read_b128 v[200:203], v177 offset:3072
	ds_read_b128 v[204:207], v177 offset:4096
	ds_read_b128 v[208:211], v177 offset:5120
	ds_read_b128 v[212:215], v177 offset:6144
	ds_read_b128 v[216:219], v177 offset:7168
	global_load_lds_dwordx4 v[178:179], off
	v_lshl_add_u64 v[178:179], s[50:51], 0, v[154:155]
	s_add_i32 m0, s37, 0xe000
	s_nop 0
	global_load_lds_dwordx4 v[178:179], off
	s_waitcnt vmcnt(8)
	s_waitcnt lgkmcnt(0)
	s_barrier
	s_setprio 1
	s_waitcnt lgkmcnt(0)
	v_mfma_f32_16x16x32_bf16 v[144:147], v[108:111], v[188:191], 0
	v_mfma_f32_16x16x32_bf16 v[140:143], v[120:123], v[188:191], 0
	v_mfma_f32_16x16x32_bf16 v[124:127], v[108:111], v[196:199], 0
	v_mfma_f32_16x16x32_bf16 v[116:119], v[120:123], v[196:199], 0
	v_mfma_f32_16x16x32_bf16 v[92:95], v[108:111], v[204:207], 0
	v_mfma_f32_16x16x32_bf16 v[88:91], v[120:123], v[204:207], 0
	v_mfma_f32_16x16x32_bf16 v[76:79], v[108:111], v[212:215], 0
	v_mfma_f32_16x16x32_bf16 v[72:75], v[120:123], v[212:215], 0
	v_mfma_f32_16x16x32_bf16 v[144:147], v[112:115], v[192:195], v[144:147]
	v_mfma_f32_16x16x32_bf16 v[140:143], v[128:131], v[192:195], v[140:143]
	v_mfma_f32_16x16x32_bf16 v[124:127], v[112:115], v[200:203], v[124:127]
	v_mfma_f32_16x16x32_bf16 v[116:119], v[128:131], v[200:203], v[116:119]
	v_mfma_f32_16x16x32_bf16 v[92:95], v[112:115], v[208:211], v[92:95]
	v_mfma_f32_16x16x32_bf16 v[88:91], v[128:131], v[208:211], v[88:91]
	v_mfma_f32_16x16x32_bf16 v[76:79], v[112:115], v[216:219], v[76:79]
	v_mfma_f32_16x16x32_bf16 v[72:75], v[128:131], v[216:219], v[72:75]
	s_setprio 0
	s_setprio 1
	v_mfma_f32_16x16x32_bf16 v[136:139], v[158:161], v[188:191], 0
	v_mfma_f32_16x16x32_bf16 v[132:135], v[166:169], v[188:191], 0
	v_mfma_f32_16x16x32_bf16 v[104:107], v[158:161], v[196:199], 0
	v_mfma_f32_16x16x32_bf16 v[100:103], v[166:169], v[196:199], 0
	v_mfma_f32_16x16x32_bf16 v[84:87], v[158:161], v[204:207], 0
	v_mfma_f32_16x16x32_bf16 v[80:83], v[166:169], v[204:207], 0
	v_mfma_f32_16x16x32_bf16 v[68:71], v[158:161], v[212:215], 0
	v_mfma_f32_16x16x32_bf16 v[64:67], v[166:169], v[212:215], 0
	v_mfma_f32_16x16x32_bf16 v[136:139], v[162:165], v[192:195], v[136:139]
	v_mfma_f32_16x16x32_bf16 v[132:135], v[170:173], v[192:195], v[132:135]
	v_mfma_f32_16x16x32_bf16 v[104:107], v[162:165], v[200:203], v[104:107]
	v_mfma_f32_16x16x32_bf16 v[100:103], v[170:173], v[200:203], v[100:103]
	v_mfma_f32_16x16x32_bf16 v[84:87], v[162:165], v[208:211], v[84:87]
	v_mfma_f32_16x16x32_bf16 v[80:83], v[170:173], v[208:211], v[80:83]
	v_mfma_f32_16x16x32_bf16 v[68:71], v[162:165], v[216:219], v[68:71]
	v_mfma_f32_16x16x32_bf16 v[64:67], v[170:173], v[216:219], v[64:67]
	s_setprio 0
	s_barrier
	s_add_i32 s20, s23, s26
	v_lshl_add_u64 v[178:179], s[52:53], 0, v[150:151]
	s_mov_b32 m0, s20
	ds_read_b128 v[188:191], v177 offset:16384
	ds_read_b128 v[192:195], v177 offset:17408
	ds_read_b128 v[196:199], v177 offset:18432
	ds_read_b128 v[200:203], v177 offset:19456
	ds_read_b128 v[204:207], v177 offset:20480
	ds_read_b128 v[208:211], v177 offset:21504
	ds_read_b128 v[212:215], v177 offset:22528
	ds_read_b128 v[216:219], v177 offset:23552
	global_load_lds_dwordx4 v[178:179], off
	s_add_i32 m0, s20, 0x2000
	s_add_u32 s20, s52, 0x40000
	v_lshl_add_u64 v[220:221], s[52:53], 0, v[96:97]
	s_addc_u32 s21, s53, 0
	s_add_i32 s23, s67, s26
	global_load_lds_dwordx4 v[220:221], off
	v_lshl_add_u64 v[228:229], s[20:21], 0, v[150:151]
	s_mov_b32 m0, s23
	v_lshl_add_u64 v[234:235], s[54:55], 0, v[148:149]
	global_load_lds_dwordx4 v[228:229], off
	v_lshl_add_u64 v[228:229], s[20:21], 0, v[96:97]
	s_add_i32 m0, s23, 0x2000
	s_nop 0
	global_load_lds_dwordx4 v[228:229], off
	v_lshl_add_u64 v[228:229], s[54:55], 0, v[152:153]
	s_mov_b32 m0, s37
	s_nop 0
	global_load_lds_dwordx4 v[228:229], off
	s_mov_b32 m0, s38
	s_nop 0
	global_load_lds_dwordx4 v[234:235], off
	s_waitcnt vmcnt(8)
	s_waitcnt lgkmcnt(0)
	s_barrier
	s_setprio 1
	s_waitcnt lgkmcnt(0)
	v_mfma_f32_16x16x32_bf16 v[60:63], v[108:111], v[188:191], 0
	v_mfma_f32_16x16x32_bf16 v[56:59], v[120:123], v[188:191], 0
	v_mfma_f32_16x16x32_bf16 v[44:47], v[108:111], v[196:199], 0
	v_mfma_f32_16x16x32_bf16 v[40:43], v[120:123], v[196:199], 0
	v_mfma_f32_16x16x32_bf16 v[28:31], v[108:111], v[204:207], 0
	v_mfma_f32_16x16x32_bf16 v[24:27], v[120:123], v[204:207], 0
	v_mfma_f32_16x16x32_bf16 v[12:15], v[108:111], v[212:215], 0
	v_mfma_f32_16x16x32_bf16 v[8:11], v[120:123], v[212:215], 0
	v_mfma_f32_16x16x32_bf16 v[60:63], v[112:115], v[192:195], v[60:63]
	v_mfma_f32_16x16x32_bf16 v[56:59], v[128:131], v[192:195], v[56:59]
	v_mfma_f32_16x16x32_bf16 v[44:47], v[112:115], v[200:203], v[44:47]
	v_mfma_f32_16x16x32_bf16 v[40:43], v[128:131], v[200:203], v[40:43]
	v_mfma_f32_16x16x32_bf16 v[28:31], v[112:115], v[208:211], v[28:31]
	v_mfma_f32_16x16x32_bf16 v[24:27], v[128:131], v[208:211], v[24:27]
	v_mfma_f32_16x16x32_bf16 v[12:15], v[112:115], v[216:219], v[12:15]
	v_mfma_f32_16x16x32_bf16 v[8:11], v[128:131], v[216:219], v[8:11]
	s_setprio 0
	s_setprio 1
	v_mfma_f32_16x16x32_bf16 v[52:55], v[158:161], v[188:191], 0
	v_mfma_f32_16x16x32_bf16 v[48:51], v[166:169], v[188:191], 0
	v_mfma_f32_16x16x32_bf16 v[36:39], v[158:161], v[196:199], 0
	v_mfma_f32_16x16x32_bf16 v[32:35], v[166:169], v[196:199], 0
	v_mfma_f32_16x16x32_bf16 v[20:23], v[158:161], v[204:207], 0
	v_mfma_f32_16x16x32_bf16 v[16:19], v[166:169], v[204:207], 0
	v_mfma_f32_16x16x32_bf16 v[4:7], v[158:161], v[212:215], 0
	v_mfma_f32_16x16x32_bf16 v[0:3], v[166:169], v[212:215], 0
	v_mfma_f32_16x16x32_bf16 v[52:55], v[162:165], v[192:195], v[52:55]
	v_mfma_f32_16x16x32_bf16 v[48:51], v[170:173], v[192:195], v[48:51]
	v_mfma_f32_16x16x32_bf16 v[36:39], v[162:165], v[200:203], v[36:39]
	v_mfma_f32_16x16x32_bf16 v[32:35], v[170:173], v[200:203], v[32:35]
	v_mfma_f32_16x16x32_bf16 v[20:23], v[162:165], v[208:211], v[20:23]
	v_mfma_f32_16x16x32_bf16 v[16:19], v[170:173], v[208:211], v[16:19]
	v_mfma_f32_16x16x32_bf16 v[4:7], v[162:165], v[216:219], v[4:7]
	v_mfma_f32_16x16x32_bf16 v[0:3], v[170:173], v[216:219], v[0:3]
	s_setprio 0
	s_barrier
	s_add_i32 s23, 0, 0x18000
	v_add_u32_e32 v98, s23, v175
	s_add_i32 s67, 0, 0x1c000
	ds_read_b128 v[108:111], v98
	ds_read_b128 v[112:115], v98 offset:1024
	ds_read_b128 v[120:123], v98 offset:2048
	ds_read_b128 v[128:131], v98 offset:3072
	v_add_u32_e32 v98, s67, v175
	ds_read_b128 v[158:161], v98
	ds_read_b128 v[162:165], v98 offset:1024
	ds_read_b128 v[166:169], v98 offset:2048
	ds_read_b128 v[170:173], v98 offset:3072
	s_add_u32 s20, s54, 0x40000
	s_addc_u32 s21, s55, 0
	s_mov_b32 m0, s39
	v_lshl_add_u64 v[236:237], s[20:21], 0, v[152:153]
	ds_read_b128 v[188:191], v177 offset:32768
	ds_read_b128 v[192:195], v177 offset:33792
	ds_read_b128 v[196:199], v177 offset:34816
	ds_read_b128 v[200:203], v177 offset:35840
	ds_read_b128 v[204:207], v177 offset:36864
	ds_read_b128 v[208:211], v177 offset:37888
	ds_read_b128 v[212:215], v177 offset:38912
	ds_read_b128 v[216:219], v177 offset:39936
	global_load_lds_dwordx4 v[236:237], off
	v_lshl_add_u64 v[236:237], s[20:21], 0, v[148:149]
	s_mov_b32 m0, s49
	s_nop 0
	global_load_lds_dwordx4 v[236:237], off
	s_waitcnt vmcnt(8)
	s_waitcnt lgkmcnt(0)
	s_barrier
	s_setprio 1
	s_waitcnt lgkmcnt(0)
	v_mfma_f32_16x16x32_bf16 v[144:147], v[108:111], v[188:191], v[144:147]
	v_mfma_f32_16x16x32_bf16 v[140:143], v[120:123], v[188:191], v[140:143]
	v_mfma_f32_16x16x32_bf16 v[124:127], v[108:111], v[196:199], v[124:127]
	v_mfma_f32_16x16x32_bf16 v[116:119], v[120:123], v[196:199], v[116:119]
	v_mfma_f32_16x16x32_bf16 v[92:95], v[108:111], v[204:207], v[92:95]
	v_mfma_f32_16x16x32_bf16 v[88:91], v[120:123], v[204:207], v[88:91]
	v_mfma_f32_16x16x32_bf16 v[76:79], v[108:111], v[212:215], v[76:79]
	v_mfma_f32_16x16x32_bf16 v[72:75], v[120:123], v[212:215], v[72:75]
	v_mfma_f32_16x16x32_bf16 v[144:147], v[112:115], v[192:195], v[144:147]
	v_mfma_f32_16x16x32_bf16 v[140:143], v[128:131], v[192:195], v[140:143]
	v_mfma_f32_16x16x32_bf16 v[124:127], v[112:115], v[200:203], v[124:127]
	v_mfma_f32_16x16x32_bf16 v[116:119], v[128:131], v[200:203], v[116:119]
	v_mfma_f32_16x16x32_bf16 v[92:95], v[112:115], v[208:211], v[92:95]
	v_mfma_f32_16x16x32_bf16 v[88:91], v[128:131], v[208:211], v[88:91]
	v_mfma_f32_16x16x32_bf16 v[76:79], v[112:115], v[216:219], v[76:79]
	v_mfma_f32_16x16x32_bf16 v[72:75], v[128:131], v[216:219], v[72:75]
	s_setprio 0
	s_setprio 1
	v_mfma_f32_16x16x32_bf16 v[136:139], v[158:161], v[188:191], v[136:139]
	v_mfma_f32_16x16x32_bf16 v[132:135], v[166:169], v[188:191], v[132:135]
	v_mfma_f32_16x16x32_bf16 v[104:107], v[158:161], v[196:199], v[104:107]
	v_mfma_f32_16x16x32_bf16 v[100:103], v[166:169], v[196:199], v[100:103]
	v_mfma_f32_16x16x32_bf16 v[84:87], v[158:161], v[204:207], v[84:87]
	v_mfma_f32_16x16x32_bf16 v[80:83], v[166:169], v[204:207], v[80:83]
	v_mfma_f32_16x16x32_bf16 v[68:71], v[158:161], v[212:215], v[68:71]
	v_mfma_f32_16x16x32_bf16 v[64:67], v[166:169], v[212:215], v[64:67]
	v_mfma_f32_16x16x32_bf16 v[136:139], v[162:165], v[192:195], v[136:139]
	v_mfma_f32_16x16x32_bf16 v[132:135], v[170:173], v[192:195], v[132:135]
	v_mfma_f32_16x16x32_bf16 v[104:107], v[162:165], v[200:203], v[104:107]
	v_mfma_f32_16x16x32_bf16 v[100:103], v[170:173], v[200:203], v[100:103]
	v_mfma_f32_16x16x32_bf16 v[84:87], v[162:165], v[208:211], v[84:87]
	v_mfma_f32_16x16x32_bf16 v[80:83], v[170:173], v[208:211], v[80:83]
	v_mfma_f32_16x16x32_bf16 v[68:71], v[162:165], v[216:219], v[68:71]
	v_mfma_f32_16x16x32_bf16 v[64:67], v[170:173], v[216:219], v[64:67]
	s_setprio 0
	s_barrier
	s_add_i32 s20, s23, s26
	v_lshl_add_u64 v[178:179], v[178:179], 0, s[30:31]
	s_mov_b32 m0, s20
	ds_read_b128 v[188:191], v177 offset:49152
	ds_read_b128 v[192:195], v177 offset:50176
	ds_read_b128 v[196:199], v177 offset:51200
	ds_read_b128 v[200:203], v177 offset:52224
	ds_read_b128 v[204:207], v177 offset:53248
	ds_read_b128 v[208:211], v177 offset:54272
	ds_read_b128 v[212:215], v177 offset:55296
	ds_read_b128 v[216:219], v177 offset:56320
	global_load_lds_dwordx4 v[178:179], off
	s_add_i32 m0, s20, 0x2000
	s_add_u32 s20, s52, 0x40080
	v_lshl_add_u64 v[178:179], v[220:221], 0, s[30:31]
	s_addc_u32 s21, s53, 0
	s_add_i32 s23, s67, s26
	global_load_lds_dwordx4 v[178:179], off
	v_lshl_add_u64 v[178:179], s[20:21], 0, v[150:151]
	s_mov_b32 m0, s23
	s_nop 0
	global_load_lds_dwordx4 v[178:179], off
	v_lshl_add_u64 v[178:179], s[20:21], 0, v[96:97]
	s_add_i32 m0, s23, 0x2000
	s_nop 0
	global_load_lds_dwordx4 v[178:179], off
	v_lshl_add_u64 v[178:179], v[228:229], 0, s[30:31]
	s_mov_b32 m0, s60
	s_nop 0
	global_load_lds_dwordx4 v[178:179], off
	v_lshl_add_u64 v[178:179], v[234:235], 0, s[30:31]
	s_mov_b32 m0, s61
	s_nop 0
	global_load_lds_dwordx4 v[178:179], off
	s_waitcnt vmcnt(8)
	s_waitcnt lgkmcnt(0)
	s_barrier
	s_setprio 1
	s_waitcnt lgkmcnt(0)
	v_mfma_f32_16x16x32_bf16 v[60:63], v[108:111], v[188:191], v[60:63]
	v_mfma_f32_16x16x32_bf16 v[56:59], v[120:123], v[188:191], v[56:59]
	v_mfma_f32_16x16x32_bf16 v[44:47], v[108:111], v[196:199], v[44:47]
	v_mfma_f32_16x16x32_bf16 v[40:43], v[120:123], v[196:199], v[40:43]
	v_mfma_f32_16x16x32_bf16 v[28:31], v[108:111], v[204:207], v[28:31]
	v_mfma_f32_16x16x32_bf16 v[24:27], v[120:123], v[204:207], v[24:27]
	v_mfma_f32_16x16x32_bf16 v[12:15], v[108:111], v[212:215], v[12:15]
	v_mfma_f32_16x16x32_bf16 v[8:11], v[120:123], v[212:215], v[8:11]
	v_mfma_f32_16x16x32_bf16 v[60:63], v[112:115], v[192:195], v[60:63]
	v_mfma_f32_16x16x32_bf16 v[56:59], v[128:131], v[192:195], v[56:59]
	v_mfma_f32_16x16x32_bf16 v[44:47], v[112:115], v[200:203], v[44:47]
	v_mfma_f32_16x16x32_bf16 v[40:43], v[128:131], v[200:203], v[40:43]
	v_mfma_f32_16x16x32_bf16 v[28:31], v[112:115], v[208:211], v[28:31]
	v_mfma_f32_16x16x32_bf16 v[24:27], v[128:131], v[208:211], v[24:27]
	v_mfma_f32_16x16x32_bf16 v[12:15], v[112:115], v[216:219], v[12:15]
	v_mfma_f32_16x16x32_bf16 v[8:11], v[128:131], v[216:219], v[8:11]
	s_setprio 0
	s_setprio 1
	v_mfma_f32_16x16x32_bf16 v[52:55], v[158:161], v[188:191], v[52:55]
	v_mfma_f32_16x16x32_bf16 v[48:51], v[166:169], v[188:191], v[48:51]
	v_mfma_f32_16x16x32_bf16 v[36:39], v[158:161], v[196:199], v[36:39]
	v_mfma_f32_16x16x32_bf16 v[32:35], v[166:169], v[196:199], v[32:35]
	v_mfma_f32_16x16x32_bf16 v[20:23], v[158:161], v[204:207], v[20:23]
	v_mfma_f32_16x16x32_bf16 v[16:19], v[166:169], v[204:207], v[16:19]
	v_mfma_f32_16x16x32_bf16 v[4:7], v[158:161], v[212:215], v[4:7]
	v_mfma_f32_16x16x32_bf16 v[0:3], v[166:169], v[212:215], v[0:3]
	v_mfma_f32_16x16x32_bf16 v[52:55], v[162:165], v[192:195], v[52:55]
	v_mfma_f32_16x16x32_bf16 v[48:51], v[170:173], v[192:195], v[48:51]
	v_mfma_f32_16x16x32_bf16 v[36:39], v[162:165], v[200:203], v[36:39]
	v_mfma_f32_16x16x32_bf16 v[32:35], v[170:173], v[200:203], v[32:35]
	v_mfma_f32_16x16x32_bf16 v[20:23], v[162:165], v[208:211], v[20:23]
	v_mfma_f32_16x16x32_bf16 v[16:19], v[170:173], v[208:211], v[16:19]
	v_mfma_f32_16x16x32_bf16 v[4:7], v[162:165], v[216:219], v[4:7]
	v_mfma_f32_16x16x32_bf16 v[0:3], v[170:173], v[216:219], v[0:3]
	s_setprio 0
	s_barrier
	s_add_i32 s66, s66, 2
	s_add_u32 s64, s64, 0x100
	s_addc_u32 s65, s65, 0
	s_add_u32 s50, s50, 0x100
	s_addc_u32 s51, s51, 0
	s_cmp_gt_u32 s66, 13
	s_cbranch_scc1 .Lpeel_exit_relu2
.LBB0_850:
	s_add_u32 s20, s50, 0xfffc0080
	s_addc_u32 s21, s51, -1
	s_add_i32 s23, 0, 0x10000
	s_cmp_eq_u32 s66, 12
	s_cselect_b32 s55, s19, s21
	s_cselect_b32 s54, s47, s20
	v_add_u32_e32 v98, s23, v175
	s_cselect_b32 s53, s17, s65
	s_cselect_b32 s52, s63, s64
	s_add_i32 s67, 0, 0x14000
	ds_read_b128 v[108:111], v98
	ds_read_b128 v[112:115], v98 offset:1024
	ds_read_b128 v[120:123], v98 offset:2048
	ds_read_b128 v[128:131], v98 offset:3072
	v_add_u32_e32 v98, s67, v175
	ds_read_b128 v[158:161], v98
	ds_read_b128 v[162:165], v98 offset:1024
	ds_read_b128 v[166:169], v98 offset:2048
	ds_read_b128 v[170:173], v98 offset:3072
	v_lshl_add_u64 v[178:179], s[50:51], 0, v[156:157]
	s_add_i32 m0, s37, 0xc000
	ds_read_b128 v[188:191], v177
	ds_read_b128 v[192:195], v177 offset:1024
	ds_read_b128 v[196:199], v177 offset:2048
	ds_read_b128 v[200:203], v177 offset:3072
	ds_read_b128 v[204:207], v177 offset:4096
	ds_read_b128 v[208:211], v177 offset:5120
	ds_read_b128 v[212:215], v177 offset:6144
	ds_read_b128 v[216:219], v177 offset:7168
	global_load_lds_dwordx4 v[178:179], off
	v_lshl_add_u64 v[178:179], s[50:51], 0, v[154:155]
	s_add_i32 m0, s37, 0xe000
	s_nop 0
	global_load_lds_dwordx4 v[178:179], off
	s_waitcnt vmcnt(8)
	s_waitcnt lgkmcnt(0)
	s_barrier
	s_setprio 1
	s_waitcnt lgkmcnt(0)
	v_mfma_f32_16x16x32_bf16 v[144:147], v[108:111], v[188:191], v[144:147]
	v_mfma_f32_16x16x32_bf16 v[140:143], v[120:123], v[188:191], v[140:143]
	v_mfma_f32_16x16x32_bf16 v[124:127], v[108:111], v[196:199], v[124:127]
	v_mfma_f32_16x16x32_bf16 v[116:119], v[120:123], v[196:199], v[116:119]
	v_mfma_f32_16x16x32_bf16 v[92:95], v[108:111], v[204:207], v[92:95]
	v_mfma_f32_16x16x32_bf16 v[88:91], v[120:123], v[204:207], v[88:91]
	v_mfma_f32_16x16x32_bf16 v[76:79], v[108:111], v[212:215], v[76:79]
	v_mfma_f32_16x16x32_bf16 v[72:75], v[120:123], v[212:215], v[72:75]
	v_mfma_f32_16x16x32_bf16 v[144:147], v[112:115], v[192:195], v[144:147]
	v_mfma_f32_16x16x32_bf16 v[140:143], v[128:131], v[192:195], v[140:143]
	v_mfma_f32_16x16x32_bf16 v[124:127], v[112:115], v[200:203], v[124:127]
	v_mfma_f32_16x16x32_bf16 v[116:119], v[128:131], v[200:203], v[116:119]
	v_mfma_f32_16x16x32_bf16 v[92:95], v[112:115], v[208:211], v[92:95]
	v_mfma_f32_16x16x32_bf16 v[88:91], v[128:131], v[208:211], v[88:91]
	v_mfma_f32_16x16x32_bf16 v[76:79], v[112:115], v[216:219], v[76:79]
	v_mfma_f32_16x16x32_bf16 v[72:75], v[128:131], v[216:219], v[72:75]
	s_setprio 0
	s_setprio 1
	v_mfma_f32_16x16x32_bf16 v[136:139], v[158:161], v[188:191], v[136:139]
	v_mfma_f32_16x16x32_bf16 v[132:135], v[166:169], v[188:191], v[132:135]
	v_mfma_f32_16x16x32_bf16 v[104:107], v[158:161], v[196:199], v[104:107]
	v_mfma_f32_16x16x32_bf16 v[100:103], v[166:169], v[196:199], v[100:103]
	v_mfma_f32_16x16x32_bf16 v[84:87], v[158:161], v[204:207], v[84:87]
	v_mfma_f32_16x16x32_bf16 v[80:83], v[166:169], v[204:207], v[80:83]
	v_mfma_f32_16x16x32_bf16 v[68:71], v[158:161], v[212:215], v[68:71]
	v_mfma_f32_16x16x32_bf16 v[64:67], v[166:169], v[212:215], v[64:67]
	v_mfma_f32_16x16x32_bf16 v[136:139], v[162:165], v[192:195], v[136:139]
	v_mfma_f32_16x16x32_bf16 v[132:135], v[170:173], v[192:195], v[132:135]
	v_mfma_f32_16x16x32_bf16 v[104:107], v[162:165], v[200:203], v[104:107]
	v_mfma_f32_16x16x32_bf16 v[100:103], v[170:173], v[200:203], v[100:103]
	v_mfma_f32_16x16x32_bf16 v[84:87], v[162:165], v[208:211], v[84:87]
	v_mfma_f32_16x16x32_bf16 v[80:83], v[170:173], v[208:211], v[80:83]
	v_mfma_f32_16x16x32_bf16 v[68:71], v[162:165], v[216:219], v[68:71]
	v_mfma_f32_16x16x32_bf16 v[64:67], v[170:173], v[216:219], v[64:67]
	s_setprio 0
	s_barrier
	s_add_i32 s20, s23, s26
	v_lshl_add_u64 v[178:179], s[52:53], 0, v[150:151]
	s_mov_b32 m0, s20
	ds_read_b128 v[188:191], v177 offset:16384
	ds_read_b128 v[192:195], v177 offset:17408
	ds_read_b128 v[196:199], v177 offset:18432
	ds_read_b128 v[200:203], v177 offset:19456
	ds_read_b128 v[204:207], v177 offset:20480
	ds_read_b128 v[208:211], v177 offset:21504
	ds_read_b128 v[212:215], v177 offset:22528
	ds_read_b128 v[216:219], v177 offset:23552
	global_load_lds_dwordx4 v[178:179], off
	s_add_i32 m0, s20, 0x2000
	s_add_u32 s20, s52, 0x40000
	v_lshl_add_u64 v[220:221], s[52:53], 0, v[96:97]
	s_addc_u32 s21, s53, 0
	s_add_i32 s23, s67, s26
	global_load_lds_dwordx4 v[220:221], off
	v_lshl_add_u64 v[228:229], s[20:21], 0, v[150:151]
	s_mov_b32 m0, s23
	v_lshl_add_u64 v[234:235], s[54:55], 0, v[148:149]
	global_load_lds_dwordx4 v[228:229], off
	v_lshl_add_u64 v[228:229], s[20:21], 0, v[96:97]
	s_add_i32 m0, s23, 0x2000
	s_nop 0
	global_load_lds_dwordx4 v[228:229], off
	v_lshl_add_u64 v[228:229], s[54:55], 0, v[152:153]
	s_mov_b32 m0, s37
	s_nop 0
	global_load_lds_dwordx4 v[228:229], off
	s_mov_b32 m0, s38
	s_nop 0
	global_load_lds_dwordx4 v[234:235], off
	s_waitcnt vmcnt(8)
	s_waitcnt lgkmcnt(0)
	s_barrier
	s_setprio 1
	s_waitcnt lgkmcnt(0)
	v_mfma_f32_16x16x32_bf16 v[60:63], v[108:111], v[188:191], v[60:63]
	v_mfma_f32_16x16x32_bf16 v[56:59], v[120:123], v[188:191], v[56:59]
	v_mfma_f32_16x16x32_bf16 v[44:47], v[108:111], v[196:199], v[44:47]
	v_mfma_f32_16x16x32_bf16 v[40:43], v[120:123], v[196:199], v[40:43]
	v_mfma_f32_16x16x32_bf16 v[28:31], v[108:111], v[204:207], v[28:31]
	v_mfma_f32_16x16x32_bf16 v[24:27], v[120:123], v[204:207], v[24:27]
	v_mfma_f32_16x16x32_bf16 v[12:15], v[108:111], v[212:215], v[12:15]
	v_mfma_f32_16x16x32_bf16 v[8:11], v[120:123], v[212:215], v[8:11]
	v_mfma_f32_16x16x32_bf16 v[60:63], v[112:115], v[192:195], v[60:63]
	v_mfma_f32_16x16x32_bf16 v[56:59], v[128:131], v[192:195], v[56:59]
	v_mfma_f32_16x16x32_bf16 v[44:47], v[112:115], v[200:203], v[44:47]
	v_mfma_f32_16x16x32_bf16 v[40:43], v[128:131], v[200:203], v[40:43]
	v_mfma_f32_16x16x32_bf16 v[28:31], v[112:115], v[208:211], v[28:31]
	v_mfma_f32_16x16x32_bf16 v[24:27], v[128:131], v[208:211], v[24:27]
	v_mfma_f32_16x16x32_bf16 v[12:15], v[112:115], v[216:219], v[12:15]
	v_mfma_f32_16x16x32_bf16 v[8:11], v[128:131], v[216:219], v[8:11]
	s_setprio 0
	s_setprio 1
	v_mfma_f32_16x16x32_bf16 v[52:55], v[158:161], v[188:191], v[52:55]
	v_mfma_f32_16x16x32_bf16 v[48:51], v[166:169], v[188:191], v[48:51]
	v_mfma_f32_16x16x32_bf16 v[36:39], v[158:161], v[196:199], v[36:39]
	v_mfma_f32_16x16x32_bf16 v[32:35], v[166:169], v[196:199], v[32:35]
	v_mfma_f32_16x16x32_bf16 v[20:23], v[158:161], v[204:207], v[20:23]
	v_mfma_f32_16x16x32_bf16 v[16:19], v[166:169], v[204:207], v[16:19]
	v_mfma_f32_16x16x32_bf16 v[4:7], v[158:161], v[212:215], v[4:7]
	v_mfma_f32_16x16x32_bf16 v[0:3], v[166:169], v[212:215], v[0:3]
	v_mfma_f32_16x16x32_bf16 v[52:55], v[162:165], v[192:195], v[52:55]
	v_mfma_f32_16x16x32_bf16 v[48:51], v[170:173], v[192:195], v[48:51]
	v_mfma_f32_16x16x32_bf16 v[36:39], v[162:165], v[200:203], v[36:39]
	v_mfma_f32_16x16x32_bf16 v[32:35], v[170:173], v[200:203], v[32:35]
	v_mfma_f32_16x16x32_bf16 v[20:23], v[162:165], v[208:211], v[20:23]
	v_mfma_f32_16x16x32_bf16 v[16:19], v[170:173], v[208:211], v[16:19]
	v_mfma_f32_16x16x32_bf16 v[4:7], v[162:165], v[216:219], v[4:7]
	v_mfma_f32_16x16x32_bf16 v[0:3], v[170:173], v[216:219], v[0:3]
	s_setprio 0
	s_barrier
	s_add_i32 s23, 0, 0x18000
	v_add_u32_e32 v98, s23, v175
	s_add_i32 s67, 0, 0x1c000
	ds_read_b128 v[108:111], v98
	ds_read_b128 v[112:115], v98 offset:1024
	ds_read_b128 v[120:123], v98 offset:2048
	ds_read_b128 v[128:131], v98 offset:3072
	v_add_u32_e32 v98, s67, v175
	ds_read_b128 v[158:161], v98
	ds_read_b128 v[162:165], v98 offset:1024
	ds_read_b128 v[166:169], v98 offset:2048
	ds_read_b128 v[170:173], v98 offset:3072
	s_add_u32 s20, s54, 0x40000
	s_addc_u32 s21, s55, 0
	s_mov_b32 m0, s39
	v_lshl_add_u64 v[236:237], s[20:21], 0, v[152:153]
	ds_read_b128 v[188:191], v177 offset:32768
	ds_read_b128 v[192:195], v177 offset:33792
	ds_read_b128 v[196:199], v177 offset:34816
	ds_read_b128 v[200:203], v177 offset:35840
	ds_read_b128 v[204:207], v177 offset:36864
	ds_read_b128 v[208:211], v177 offset:37888
	ds_read_b128 v[212:215], v177 offset:38912
	ds_read_b128 v[216:219], v177 offset:39936
	global_load_lds_dwordx4 v[236:237], off
	v_lshl_add_u64 v[236:237], s[20:21], 0, v[148:149]
	s_mov_b32 m0, s49
	s_nop 0
	global_load_lds_dwordx4 v[236:237], off
	s_waitcnt vmcnt(8)
	s_waitcnt lgkmcnt(0)
	s_barrier
	s_setprio 1
	s_waitcnt lgkmcnt(0)
	v_mfma_f32_16x16x32_bf16 v[144:147], v[108:111], v[188:191], v[144:147]
	v_mfma_f32_16x16x32_bf16 v[140:143], v[120:123], v[188:191], v[140:143]
	v_mfma_f32_16x16x32_bf16 v[124:127], v[108:111], v[196:199], v[124:127]
	v_mfma_f32_16x16x32_bf16 v[116:119], v[120:123], v[196:199], v[116:119]
	v_mfma_f32_16x16x32_bf16 v[92:95], v[108:111], v[204:207], v[92:95]
	v_mfma_f32_16x16x32_bf16 v[88:91], v[120:123], v[204:207], v[88:91]
	v_mfma_f32_16x16x32_bf16 v[76:79], v[108:111], v[212:215], v[76:79]
	v_mfma_f32_16x16x32_bf16 v[72:75], v[120:123], v[212:215], v[72:75]
	v_mfma_f32_16x16x32_bf16 v[144:147], v[112:115], v[192:195], v[144:147]
	v_mfma_f32_16x16x32_bf16 v[140:143], v[128:131], v[192:195], v[140:143]
	v_mfma_f32_16x16x32_bf16 v[124:127], v[112:115], v[200:203], v[124:127]
	v_mfma_f32_16x16x32_bf16 v[116:119], v[128:131], v[200:203], v[116:119]
	v_mfma_f32_16x16x32_bf16 v[92:95], v[112:115], v[208:211], v[92:95]
	v_mfma_f32_16x16x32_bf16 v[88:91], v[128:131], v[208:211], v[88:91]
	v_mfma_f32_16x16x32_bf16 v[76:79], v[112:115], v[216:219], v[76:79]
	v_mfma_f32_16x16x32_bf16 v[72:75], v[128:131], v[216:219], v[72:75]
	s_setprio 0
	s_setprio 1
	v_mfma_f32_16x16x32_bf16 v[136:139], v[158:161], v[188:191], v[136:139]
	v_mfma_f32_16x16x32_bf16 v[132:135], v[166:169], v[188:191], v[132:135]
	v_mfma_f32_16x16x32_bf16 v[104:107], v[158:161], v[196:199], v[104:107]
	v_mfma_f32_16x16x32_bf16 v[100:103], v[166:169], v[196:199], v[100:103]
	v_mfma_f32_16x16x32_bf16 v[84:87], v[158:161], v[204:207], v[84:87]
	v_mfma_f32_16x16x32_bf16 v[80:83], v[166:169], v[204:207], v[80:83]
	v_mfma_f32_16x16x32_bf16 v[68:71], v[158:161], v[212:215], v[68:71]
	v_mfma_f32_16x16x32_bf16 v[64:67], v[166:169], v[212:215], v[64:67]
	v_mfma_f32_16x16x32_bf16 v[136:139], v[162:165], v[192:195], v[136:139]
	v_mfma_f32_16x16x32_bf16 v[132:135], v[170:173], v[192:195], v[132:135]
	v_mfma_f32_16x16x32_bf16 v[104:107], v[162:165], v[200:203], v[104:107]
	v_mfma_f32_16x16x32_bf16 v[100:103], v[170:173], v[200:203], v[100:103]
	v_mfma_f32_16x16x32_bf16 v[84:87], v[162:165], v[208:211], v[84:87]
	v_mfma_f32_16x16x32_bf16 v[80:83], v[170:173], v[208:211], v[80:83]
	v_mfma_f32_16x16x32_bf16 v[68:71], v[162:165], v[216:219], v[68:71]
	v_mfma_f32_16x16x32_bf16 v[64:67], v[170:173], v[216:219], v[64:67]
	s_setprio 0
	s_barrier
	s_add_i32 s20, s23, s26
	v_lshl_add_u64 v[178:179], v[178:179], 0, s[30:31]
	s_mov_b32 m0, s20
	ds_read_b128 v[188:191], v177 offset:49152
	ds_read_b128 v[192:195], v177 offset:50176
	ds_read_b128 v[196:199], v177 offset:51200
	ds_read_b128 v[200:203], v177 offset:52224
	ds_read_b128 v[204:207], v177 offset:53248
	ds_read_b128 v[208:211], v177 offset:54272
	ds_read_b128 v[212:215], v177 offset:55296
	ds_read_b128 v[216:219], v177 offset:56320
	global_load_lds_dwordx4 v[178:179], off
	s_add_i32 m0, s20, 0x2000
	s_add_u32 s20, s52, 0x40080
	v_lshl_add_u64 v[178:179], v[220:221], 0, s[30:31]
	s_addc_u32 s21, s53, 0
	s_add_i32 s23, s67, s26
	global_load_lds_dwordx4 v[178:179], off
	v_lshl_add_u64 v[178:179], s[20:21], 0, v[150:151]
	s_mov_b32 m0, s23
	s_nop 0
	global_load_lds_dwordx4 v[178:179], off
	v_lshl_add_u64 v[178:179], s[20:21], 0, v[96:97]
	s_add_i32 m0, s23, 0x2000
	s_nop 0
	global_load_lds_dwordx4 v[178:179], off
	v_lshl_add_u64 v[178:179], v[228:229], 0, s[30:31]
	s_mov_b32 m0, s60
	s_nop 0
	global_load_lds_dwordx4 v[178:179], off
	v_lshl_add_u64 v[178:179], v[234:235], 0, s[30:31]
	s_mov_b32 m0, s61
	s_nop 0
	global_load_lds_dwordx4 v[178:179], off
	s_waitcnt vmcnt(8)
	s_waitcnt lgkmcnt(0)
	s_barrier
	s_setprio 1
	s_waitcnt lgkmcnt(0)
	v_mfma_f32_16x16x32_bf16 v[60:63], v[108:111], v[188:191], v[60:63]
	v_mfma_f32_16x16x32_bf16 v[56:59], v[120:123], v[188:191], v[56:59]
	v_mfma_f32_16x16x32_bf16 v[44:47], v[108:111], v[196:199], v[44:47]
	v_mfma_f32_16x16x32_bf16 v[40:43], v[120:123], v[196:199], v[40:43]
	v_mfma_f32_16x16x32_bf16 v[28:31], v[108:111], v[204:207], v[28:31]
	v_mfma_f32_16x16x32_bf16 v[24:27], v[120:123], v[204:207], v[24:27]
	v_mfma_f32_16x16x32_bf16 v[12:15], v[108:111], v[212:215], v[12:15]
	v_mfma_f32_16x16x32_bf16 v[8:11], v[120:123], v[212:215], v[8:11]
	v_mfma_f32_16x16x32_bf16 v[60:63], v[112:115], v[192:195], v[60:63]
	v_mfma_f32_16x16x32_bf16 v[56:59], v[128:131], v[192:195], v[56:59]
	v_mfma_f32_16x16x32_bf16 v[44:47], v[112:115], v[200:203], v[44:47]
	v_mfma_f32_16x16x32_bf16 v[40:43], v[128:131], v[200:203], v[40:43]
	v_mfma_f32_16x16x32_bf16 v[28:31], v[112:115], v[208:211], v[28:31]
	v_mfma_f32_16x16x32_bf16 v[24:27], v[128:131], v[208:211], v[24:27]
	v_mfma_f32_16x16x32_bf16 v[12:15], v[112:115], v[216:219], v[12:15]
	v_mfma_f32_16x16x32_bf16 v[8:11], v[128:131], v[216:219], v[8:11]
	s_setprio 0
	s_setprio 1
	v_mfma_f32_16x16x32_bf16 v[52:55], v[158:161], v[188:191], v[52:55]
	v_mfma_f32_16x16x32_bf16 v[48:51], v[166:169], v[188:191], v[48:51]
	v_mfma_f32_16x16x32_bf16 v[36:39], v[158:161], v[196:199], v[36:39]
	v_mfma_f32_16x16x32_bf16 v[32:35], v[166:169], v[196:199], v[32:35]
	v_mfma_f32_16x16x32_bf16 v[20:23], v[158:161], v[204:207], v[20:23]
	v_mfma_f32_16x16x32_bf16 v[16:19], v[166:169], v[204:207], v[16:19]
	v_mfma_f32_16x16x32_bf16 v[4:7], v[158:161], v[212:215], v[4:7]
	v_mfma_f32_16x16x32_bf16 v[0:3], v[166:169], v[212:215], v[0:3]
	v_mfma_f32_16x16x32_bf16 v[52:55], v[162:165], v[192:195], v[52:55]
	v_mfma_f32_16x16x32_bf16 v[48:51], v[170:173], v[192:195], v[48:51]
	v_mfma_f32_16x16x32_bf16 v[36:39], v[162:165], v[200:203], v[36:39]
	v_mfma_f32_16x16x32_bf16 v[32:35], v[170:173], v[200:203], v[32:35]
	v_mfma_f32_16x16x32_bf16 v[20:23], v[162:165], v[208:211], v[20:23]
	v_mfma_f32_16x16x32_bf16 v[16:19], v[170:173], v[208:211], v[16:19]
	v_mfma_f32_16x16x32_bf16 v[4:7], v[162:165], v[216:219], v[4:7]
	v_mfma_f32_16x16x32_bf16 v[0:3], v[170:173], v[216:219], v[0:3]
	s_setprio 0
	s_barrier
	s_add_i32 s66, s66, 2
	s_add_u32 s64, s64, 0x100
	s_addc_u32 s65, s65, 0
	s_add_u32 s50, s50, 0x100
	s_addc_u32 s51, s51, 0
	s_cmp_gt_u32 s66, 13
	s_cbranch_scc0 .LBB0_850
.Lpeel_exit_relu2:
	s_and_b64 vcc, exec, s[14:15]
	s_cbranch_vccz .LBB0_853
	s_barrier
.LBB0_853:
	s_lshl_b32 s17, s48, 8
	s_and_b32 s19, s17, 0xfffff000
	s_cmpk_lt_i32 s48, 0x80
	s_cselect_b32 s20, s19, 0x8000
	s_ashr_i32 s21, s20, 31
	s_lshl_b64 s[20:21], s[20:21], 2
	v_lshl_or_b32 v160, s46, 8, v176
	s_add_u32 s20, s56, s20
	s_addc_u32 s21, s57, s21
	v_ashrrev_i32_e32 v161, 31, v160
	v_add_u32_e32 v178, s17, v174
	v_lshl_add_u64 v[112:113], v[160:161], 2, s[20:21]
	v_mov_b32_e32 v158, v178
	global_load_dwordx4 v[120:123], v[112:113], off offset:16
	global_load_dwordx4 v[128:131], v[112:113], off
	global_load_dwordx4 v[108:111], v[112:113], off offset:528
	s_nop 0
	global_load_dwordx4 v[112:115], v[112:113], off offset:512
	v_or_b32_e32 v172, 16, v178
	v_ashrrev_i32_e32 v159, 31, v158
	v_lshl_add_u64 v[158:159], v[158:159], 2, s[6:7]
	global_load_dword v98, v[158:159], off
	v_mov_b32_e32 v158, v172
	v_or_b32_e32 v170, 32, v178
	v_ashrrev_i32_e32 v159, 31, v158
	v_lshl_add_u64 v[158:159], v[158:159], 2, s[6:7]
	global_load_dword v173, v[158:159], off
	v_mov_b32_e32 v158, v170
	v_or_b32_e32 v168, 48, v178
	v_ashrrev_i32_e32 v159, 31, v158
	v_lshl_add_u64 v[158:159], v[158:159], 2, s[6:7]
	global_load_dword v171, v[158:159], off
	v_mov_b32_e32 v158, v168
	v_add_u32_e32 v166, 0x80, v178
	v_ashrrev_i32_e32 v159, 31, v158
	v_lshl_add_u64 v[158:159], v[158:159], 2, s[6:7]
	global_load_dword v169, v[158:159], off
	v_mov_b32_e32 v158, v166
	v_add_u32_e32 v164, 0x90, v178
	v_ashrrev_i32_e32 v159, 31, v158
	v_lshl_add_u64 v[158:159], v[158:159], 2, s[6:7]
	global_load_dword v167, v[158:159], off
	v_mov_b32_e32 v158, v164
	v_add_u32_e32 v162, 0xa0, v178
	v_ashrrev_i32_e32 v159, 31, v158
	v_lshl_add_u64 v[158:159], v[158:159], 2, s[6:7]
	global_load_dword v165, v[158:159], off
	v_mov_b32_e32 v158, v162
	v_lshlrev_b64 v[160:161], 1, v[160:161]
	v_ashrrev_i32_e32 v159, 31, v158
	v_lshl_add_u64 v[158:159], v[158:159], 2, s[6:7]
	global_load_dword v163, v[158:159], off
	v_add_u32_e32 v158, 0xb0, v178
	v_mov_b32_e32 v188, v158
	s_mov_b64 s[46:47], -1
	v_ashrrev_i32_e32 v189, 31, v188
	v_lshl_add_u64 v[188:189], v[188:189], 2, s[6:7]
	global_load_dword v159, v[188:189], off
	s_waitcnt vmcnt(0)
	v_fmamk_f32 v98, v98, 0x3a800000, v223
	v_cmp_gt_f32_e32 vcc, s29, v98
	v_mul_f32_e32 v179, 0x4b800000, v98
	s_nop 0
	v_cndmask_b32_e32 v98, v98, v179, vcc
	v_rsq_f32_e32 v98, v98
	s_nop 0
	v_mul_f32_e32 v179, 0x45800000, v98
	v_cndmask_b32_e32 v98, v98, v179, vcc
	v_pk_fma_f32 v[140:141], v[140:141], v[98:99], v[120:121] op_sel_hi:[1,0,1]
	v_ashrrev_i32_e32 v179, 31, v178
	v_pk_fma_f32 v[146:147], v[146:147], v[98:99], v[130:131] op_sel_hi:[1,0,1]
	v_pk_fma_f32 v[144:145], v[144:145], v[98:99], v[128:129] op_sel_hi:[1,0,1]
	v_pk_fma_f32 v[142:143], v[142:143], v[98:99], v[122:123] op_sel_hi:[1,0,1]
	v_max_f32_e32 v140, 0, v140
	v_max_f32_e32 v141, 0, v141
	v_lshlrev_b64 v[178:179], 13, v[178:179]
	v_max_f32_e32 v144, 0, v144
	v_max_f32_e32 v145, 0, v145
	v_pk_mul_f32 v[188:189], v[140:141], v[140:141]
	v_max_f32_e32 v140, 0, v146
	v_max_f32_e32 v142, 0, v142
	v_max_f32_e32 v141, 0, v147
	v_max_f32_e32 v143, 0, v143
	v_lshl_add_u64 v[178:179], s[90:91], 0, v[178:179]
	v_pk_mul_f32 v[144:145], v[144:145], v[144:145]
	v_pk_mul_f32 v[146:147], v[140:141], v[140:141]
	v_pk_mul_f32 v[190:191], v[142:143], v[142:143]
	v_pk_fma_f32 v[132:133], v[132:133], v[98:99], v[108:109] op_sel_hi:[1,0,1]
	v_lshl_add_u64 v[178:179], v[178:179], 0, v[160:161]
	v_cvt_pk_bf16_f32 v140, v144, v145
	v_cvt_pk_bf16_f32 v141, v146, v147
	v_cvt_pk_bf16_f32 v142, v188, v189
	v_cvt_pk_bf16_f32 v143, v190, v191
	v_pk_fma_f32 v[138:139], v[138:139], v[98:99], v[114:115] op_sel_hi:[1,0,1]
	v_pk_fma_f32 v[136:137], v[136:137], v[98:99], v[112:113] op_sel_hi:[1,0,1]
	v_pk_fma_f32 v[134:135], v[134:135], v[98:99], v[110:111] op_sel_hi:[1,0,1]
	v_max_f32_e32 v132, 0, v132
	v_max_f32_e32 v133, 0, v133
	global_store_dwordx4 v[178:179], v[140:143], off
	v_max_f32_e32 v136, 0, v136
	v_max_f32_e32 v137, 0, v137
	v_pk_mul_f32 v[140:141], v[132:133], v[132:133]
	v_max_f32_e32 v132, 0, v138
	v_max_f32_e32 v134, 0, v134
	v_max_f32_e32 v133, 0, v139
	v_max_f32_e32 v135, 0, v135
	v_pk_mul_f32 v[136:137], v[136:137], v[136:137]
	v_pk_mul_f32 v[138:139], v[132:133], v[132:133]
	v_pk_mul_f32 v[142:143], v[134:135], v[134:135]
	v_cvt_pk_bf16_f32 v132, v136, v137
	v_cvt_pk_bf16_f32 v133, v138, v139
	v_cvt_pk_bf16_f32 v134, v140, v141
	v_cvt_pk_bf16_f32 v135, v142, v143
	v_fmamk_f32 v98, v173, 0x3a800000, v223
	global_store_dwordx4 v[178:179], v[132:135], off offset:256
	v_cmp_gt_f32_e32 vcc, s29, v98
	s_nop 0
	v_mul_f32_e32 v132, 0x4b800000, v98
	v_cndmask_b32_e32 v98, v98, v132, vcc
	v_rsq_f32_e32 v98, v98
	v_ashrrev_i32_e32 v173, 31, v172
	v_mul_f32_e32 v132, 0x45800000, v98
	v_cndmask_b32_e32 v98, v98, v132, vcc
	v_pk_fma_f32 v[116:117], v[116:117], v[98:99], v[120:121] op_sel_hi:[1,0,1]
	v_pk_fma_f32 v[126:127], v[126:127], v[98:99], v[130:131] op_sel_hi:[1,0,1]
	v_pk_fma_f32 v[124:125], v[124:125], v[98:99], v[128:129] op_sel_hi:[1,0,1]
	v_pk_fma_f32 v[118:119], v[118:119], v[98:99], v[122:123] op_sel_hi:[1,0,1]
	v_max_f32_e32 v116, 0, v116
	v_max_f32_e32 v117, 0, v117
	v_lshlrev_b64 v[132:133], 13, v[172:173]
	v_max_f32_e32 v124, 0, v124
	v_max_f32_e32 v125, 0, v125
	v_pk_mul_f32 v[134:135], v[116:117], v[116:117]
	v_max_f32_e32 v116, 0, v126
	v_max_f32_e32 v118, 0, v118
	v_max_f32_e32 v117, 0, v127
	v_max_f32_e32 v119, 0, v119
	v_lshl_add_u64 v[132:133], s[90:91], 0, v[132:133]
	v_pk_mul_f32 v[124:125], v[124:125], v[124:125]
	v_pk_mul_f32 v[126:127], v[116:117], v[116:117]
	v_pk_mul_f32 v[136:137], v[118:119], v[118:119]
	v_pk_fma_f32 v[100:101], v[100:101], v[98:99], v[108:109] op_sel_hi:[1,0,1]
	v_lshl_add_u64 v[132:133], v[132:133], 0, v[160:161]
	v_cvt_pk_bf16_f32 v116, v124, v125
	v_cvt_pk_bf16_f32 v117, v126, v127
	v_cvt_pk_bf16_f32 v118, v134, v135
	v_cvt_pk_bf16_f32 v119, v136, v137
	v_pk_fma_f32 v[106:107], v[106:107], v[98:99], v[114:115] op_sel_hi:[1,0,1]
	v_pk_fma_f32 v[104:105], v[104:105], v[98:99], v[112:113] op_sel_hi:[1,0,1]
	v_pk_fma_f32 v[102:103], v[102:103], v[98:99], v[110:111] op_sel_hi:[1,0,1]
	v_max_f32_e32 v100, 0, v100
	v_max_f32_e32 v101, 0, v101
	global_store_dwordx4 v[132:133], v[116:119], off
	v_max_f32_e32 v104, 0, v104
	v_max_f32_e32 v105, 0, v105
	v_pk_mul_f32 v[116:117], v[100:101], v[100:101]
	v_max_f32_e32 v100, 0, v106
	v_max_f32_e32 v102, 0, v102
	v_max_f32_e32 v101, 0, v107
	v_max_f32_e32 v103, 0, v103
	v_pk_mul_f32 v[104:105], v[104:105], v[104:105]
	v_pk_mul_f32 v[106:107], v[100:101], v[100:101]
	v_pk_mul_f32 v[118:119], v[102:103], v[102:103]
	v_cvt_pk_bf16_f32 v100, v104, v105
	v_cvt_pk_bf16_f32 v101, v106, v107
	v_cvt_pk_bf16_f32 v102, v116, v117
	v_cvt_pk_bf16_f32 v103, v118, v119
	v_fmamk_f32 v98, v171, 0x3a800000, v223
	global_store_dwordx4 v[132:133], v[100:103], off offset:256
	v_cmp_gt_f32_e32 vcc, s29, v98
	s_nop 0
	v_mul_f32_e32 v100, 0x4b800000, v98
	v_cndmask_b32_e32 v98, v98, v100, vcc
	v_rsq_f32_e32 v98, v98
	v_ashrrev_i32_e32 v171, 31, v170
	v_mul_f32_e32 v100, 0x45800000, v98
	v_cndmask_b32_e32 v98, v98, v100, vcc
	v_pk_fma_f32 v[88:89], v[88:89], v[98:99], v[120:121] op_sel_hi:[1,0,1]
	v_pk_fma_f32 v[94:95], v[94:95], v[98:99], v[130:131] op_sel_hi:[1,0,1]
	v_pk_fma_f32 v[92:93], v[92:93], v[98:99], v[128:129] op_sel_hi:[1,0,1]
	v_pk_fma_f32 v[90:91], v[90:91], v[98:99], v[122:123] op_sel_hi:[1,0,1]
	v_max_f32_e32 v88, 0, v88
	v_max_f32_e32 v89, 0, v89
	v_lshlrev_b64 v[100:101], 13, v[170:171]
	v_max_f32_e32 v92, 0, v92
	v_max_f32_e32 v93, 0, v93
	v_pk_mul_f32 v[102:103], v[88:89], v[88:89]
	v_max_f32_e32 v88, 0, v94
	v_max_f32_e32 v90, 0, v90
	v_max_f32_e32 v89, 0, v95
	v_max_f32_e32 v91, 0, v91
	v_lshl_add_u64 v[100:101], s[90:91], 0, v[100:101]
	v_pk_mul_f32 v[92:93], v[92:93], v[92:93]
	v_pk_mul_f32 v[94:95], v[88:89], v[88:89]
	v_pk_mul_f32 v[104:105], v[90:91], v[90:91]
	v_pk_fma_f32 v[80:81], v[80:81], v[98:99], v[108:109] op_sel_hi:[1,0,1]
	v_lshl_add_u64 v[100:101], v[100:101], 0, v[160:161]
	v_cvt_pk_bf16_f32 v88, v92, v93
	v_cvt_pk_bf16_f32 v89, v94, v95
	v_cvt_pk_bf16_f32 v90, v102, v103
	v_cvt_pk_bf16_f32 v91, v104, v105
	v_pk_fma_f32 v[86:87], v[86:87], v[98:99], v[114:115] op_sel_hi:[1,0,1]
	v_pk_fma_f32 v[84:85], v[84:85], v[98:99], v[112:113] op_sel_hi:[1,0,1]
	v_pk_fma_f32 v[82:83], v[82:83], v[98:99], v[110:111] op_sel_hi:[1,0,1]
	v_max_f32_e32 v80, 0, v80
	v_max_f32_e32 v81, 0, v81
	global_store_dwordx4 v[100:101], v[88:91], off
	v_max_f32_e32 v84, 0, v84
	v_max_f32_e32 v85, 0, v85
	v_pk_mul_f32 v[88:89], v[80:81], v[80:81]
	v_max_f32_e32 v80, 0, v86
	v_max_f32_e32 v82, 0, v82
	v_max_f32_e32 v81, 0, v87
	v_max_f32_e32 v83, 0, v83
	v_pk_mul_f32 v[84:85], v[84:85], v[84:85]
	v_pk_mul_f32 v[86:87], v[80:81], v[80:81]
	v_pk_mul_f32 v[90:91], v[82:83], v[82:83]
	v_cvt_pk_bf16_f32 v80, v84, v85
	v_cvt_pk_bf16_f32 v81, v86, v87
	v_cvt_pk_bf16_f32 v82, v88, v89
	v_cvt_pk_bf16_f32 v83, v90, v91
	global_store_dwordx4 v[100:101], v[80:83], off offset:256
	s_nop 1
	v_fmamk_f32 v80, v169, 0x3a800000, v223
	v_cmp_gt_f32_e32 vcc, s29, v80
	v_mul_f32_e32 v81, 0x4b800000, v80
	v_ashrrev_i32_e32 v169, 31, v168
	v_cndmask_b32_e32 v80, v80, v81, vcc
	v_rsq_f32_e32 v80, v80
	v_lshlrev_b64 v[82:83], 13, v[168:169]
	v_lshl_add_u64 v[82:83], s[90:91], 0, v[82:83]
	v_lshl_add_u64 v[82:83], v[82:83], 0, v[160:161]
	v_mul_f32_e32 v81, 0x45800000, v80
	v_cndmask_b32_e32 v80, v80, v81, vcc
	v_pk_fma_f32 v[72:73], v[72:73], v[80:81], v[120:121] op_sel_hi:[1,0,1]
	v_pk_fma_f32 v[78:79], v[78:79], v[80:81], v[130:131] op_sel_hi:[1,0,1]
	v_pk_fma_f32 v[76:77], v[76:77], v[80:81], v[128:129] op_sel_hi:[1,0,1]
	v_pk_fma_f32 v[74:75], v[74:75], v[80:81], v[122:123] op_sel_hi:[1,0,1]
	v_max_f32_e32 v72, 0, v72
	v_max_f32_e32 v73, 0, v73
	v_max_f32_e32 v76, 0, v76
	v_max_f32_e32 v77, 0, v77
	v_pk_mul_f32 v[84:85], v[72:73], v[72:73]
	v_max_f32_e32 v72, 0, v78
	v_max_f32_e32 v74, 0, v74
	v_max_f32_e32 v73, 0, v79
	v_max_f32_e32 v75, 0, v75
	v_pk_mul_f32 v[76:77], v[76:77], v[76:77]
	v_pk_mul_f32 v[78:79], v[72:73], v[72:73]
	v_pk_mul_f32 v[86:87], v[74:75], v[74:75]
	v_pk_fma_f32 v[64:65], v[64:65], v[80:81], v[108:109] op_sel_hi:[1,0,1]
	v_cvt_pk_bf16_f32 v72, v76, v77
	v_cvt_pk_bf16_f32 v73, v78, v79
	v_cvt_pk_bf16_f32 v74, v84, v85
	v_cvt_pk_bf16_f32 v75, v86, v87
	v_pk_fma_f32 v[70:71], v[70:71], v[80:81], v[114:115] op_sel_hi:[1,0,1]
	v_pk_fma_f32 v[68:69], v[68:69], v[80:81], v[112:113] op_sel_hi:[1,0,1]
	v_pk_fma_f32 v[66:67], v[66:67], v[80:81], v[110:111] op_sel_hi:[1,0,1]
	v_max_f32_e32 v64, 0, v64
	v_max_f32_e32 v65, 0, v65
	global_store_dwordx4 v[82:83], v[72:75], off
	v_max_f32_e32 v68, 0, v68
	v_max_f32_e32 v69, 0, v69
	v_pk_mul_f32 v[72:73], v[64:65], v[64:65]
	v_max_f32_e32 v64, 0, v70
	v_max_f32_e32 v66, 0, v66
	v_max_f32_e32 v65, 0, v71
	v_max_f32_e32 v67, 0, v67
	v_pk_mul_f32 v[68:69], v[68:69], v[68:69]
	v_pk_mul_f32 v[70:71], v[64:65], v[64:65]
	v_pk_mul_f32 v[74:75], v[66:67], v[66:67]
	v_cvt_pk_bf16_f32 v64, v68, v69
	v_cvt_pk_bf16_f32 v65, v70, v71
	v_cvt_pk_bf16_f32 v66, v72, v73
	v_cvt_pk_bf16_f32 v67, v74, v75
	global_store_dwordx4 v[82:83], v[64:67], off offset:256
	s_nop 1
	v_fmamk_f32 v64, v167, 0x3a800000, v223
	v_cmp_gt_f32_e32 vcc, s29, v64
	v_mul_f32_e32 v65, 0x4b800000, v64
	v_ashrrev_i32_e32 v167, 31, v166
	v_cndmask_b32_e32 v64, v64, v65, vcc
	v_rsq_f32_e32 v64, v64
	v_lshlrev_b64 v[66:67], 13, v[166:167]
	v_lshl_add_u64 v[66:67], s[90:91], 0, v[66:67]
	v_lshl_add_u64 v[66:67], v[66:67], 0, v[160:161]
	v_mul_f32_e32 v65, 0x45800000, v64
	v_cndmask_b32_e32 v64, v64, v65, vcc
	v_pk_fma_f32 v[56:57], v[56:57], v[64:65], v[120:121] op_sel_hi:[1,0,1]
	v_pk_fma_f32 v[62:63], v[62:63], v[64:65], v[130:131] op_sel_hi:[1,0,1]
	v_pk_fma_f32 v[60:61], v[60:61], v[64:65], v[128:129] op_sel_hi:[1,0,1]
	v_pk_fma_f32 v[58:59], v[58:59], v[64:65], v[122:123] op_sel_hi:[1,0,1]
	v_max_f32_e32 v56, 0, v56
	v_max_f32_e32 v57, 0, v57
	v_max_f32_e32 v60, 0, v60
	v_max_f32_e32 v61, 0, v61
	v_pk_mul_f32 v[68:69], v[56:57], v[56:57]
	v_max_f32_e32 v56, 0, v62
	v_max_f32_e32 v58, 0, v58
	v_max_f32_e32 v57, 0, v63
	v_max_f32_e32 v59, 0, v59
	v_pk_mul_f32 v[60:61], v[60:61], v[60:61]
	v_pk_mul_f32 v[62:63], v[56:57], v[56:57]
	v_pk_mul_f32 v[70:71], v[58:59], v[58:59]
	v_pk_fma_f32 v[48:49], v[48:49], v[64:65], v[108:109] op_sel_hi:[1,0,1]
	v_cvt_pk_bf16_f32 v56, v60, v61
	v_cvt_pk_bf16_f32 v57, v62, v63
	v_cvt_pk_bf16_f32 v58, v68, v69
	v_cvt_pk_bf16_f32 v59, v70, v71
	v_pk_fma_f32 v[54:55], v[54:55], v[64:65], v[114:115] op_sel_hi:[1,0,1]
	v_pk_fma_f32 v[52:53], v[52:53], v[64:65], v[112:113] op_sel_hi:[1,0,1]
	v_pk_fma_f32 v[50:51], v[50:51], v[64:65], v[110:111] op_sel_hi:[1,0,1]
	v_max_f32_e32 v48, 0, v48
	v_max_f32_e32 v49, 0, v49
	global_store_dwordx4 v[66:67], v[56:59], off
	v_max_f32_e32 v52, 0, v52
	v_max_f32_e32 v53, 0, v53
	v_pk_mul_f32 v[56:57], v[48:49], v[48:49]
	v_max_f32_e32 v48, 0, v54
	v_max_f32_e32 v50, 0, v50
	v_max_f32_e32 v49, 0, v55
	v_max_f32_e32 v51, 0, v51
	v_pk_mul_f32 v[52:53], v[52:53], v[52:53]
	v_pk_mul_f32 v[54:55], v[48:49], v[48:49]
	v_pk_mul_f32 v[58:59], v[50:51], v[50:51]
	v_cvt_pk_bf16_f32 v48, v52, v53
	v_cvt_pk_bf16_f32 v49, v54, v55
	v_cvt_pk_bf16_f32 v50, v56, v57
	v_cvt_pk_bf16_f32 v51, v58, v59
	global_store_dwordx4 v[66:67], v[48:51], off offset:256
	s_nop 1
	v_fmamk_f32 v48, v165, 0x3a800000, v223
	v_cmp_gt_f32_e32 vcc, s29, v48
	v_mul_f32_e32 v49, 0x4b800000, v48
	v_ashrrev_i32_e32 v165, 31, v164
	v_cndmask_b32_e32 v48, v48, v49, vcc
	v_rsq_f32_e32 v48, v48
	v_lshlrev_b64 v[50:51], 13, v[164:165]
	v_lshl_add_u64 v[50:51], s[90:91], 0, v[50:51]
	v_lshl_add_u64 v[50:51], v[50:51], 0, v[160:161]
	v_mul_f32_e32 v49, 0x45800000, v48
	v_cndmask_b32_e32 v48, v48, v49, vcc
	v_pk_fma_f32 v[40:41], v[40:41], v[48:49], v[120:121] op_sel_hi:[1,0,1]
	v_pk_fma_f32 v[46:47], v[46:47], v[48:49], v[130:131] op_sel_hi:[1,0,1]
	v_pk_fma_f32 v[44:45], v[44:45], v[48:49], v[128:129] op_sel_hi:[1,0,1]
	v_pk_fma_f32 v[42:43], v[42:43], v[48:49], v[122:123] op_sel_hi:[1,0,1]
	v_max_f32_e32 v40, 0, v40
	v_max_f32_e32 v41, 0, v41
	v_max_f32_e32 v44, 0, v44
	v_max_f32_e32 v45, 0, v45
	v_pk_mul_f32 v[52:53], v[40:41], v[40:41]
	v_max_f32_e32 v40, 0, v46
	v_max_f32_e32 v42, 0, v42
	v_max_f32_e32 v41, 0, v47
	v_max_f32_e32 v43, 0, v43
	v_pk_mul_f32 v[44:45], v[44:45], v[44:45]
	v_pk_mul_f32 v[46:47], v[40:41], v[40:41]
	v_pk_mul_f32 v[54:55], v[42:43], v[42:43]
	v_pk_fma_f32 v[32:33], v[32:33], v[48:49], v[108:109] op_sel_hi:[1,0,1]
	v_cvt_pk_bf16_f32 v40, v44, v45
	v_cvt_pk_bf16_f32 v41, v46, v47
	v_cvt_pk_bf16_f32 v42, v52, v53
	v_cvt_pk_bf16_f32 v43, v54, v55
	v_pk_fma_f32 v[38:39], v[38:39], v[48:49], v[114:115] op_sel_hi:[1,0,1]
	v_pk_fma_f32 v[36:37], v[36:37], v[48:49], v[112:113] op_sel_hi:[1,0,1]
	v_pk_fma_f32 v[34:35], v[34:35], v[48:49], v[110:111] op_sel_hi:[1,0,1]
	v_max_f32_e32 v32, 0, v32
	v_max_f32_e32 v33, 0, v33
	global_store_dwordx4 v[50:51], v[40:43], off
	v_max_f32_e32 v36, 0, v36
	v_max_f32_e32 v37, 0, v37
	v_pk_mul_f32 v[40:41], v[32:33], v[32:33]
	v_max_f32_e32 v32, 0, v38
	v_max_f32_e32 v34, 0, v34
	v_max_f32_e32 v33, 0, v39
	v_max_f32_e32 v35, 0, v35
	v_pk_mul_f32 v[36:37], v[36:37], v[36:37]
	v_pk_mul_f32 v[38:39], v[32:33], v[32:33]
	v_pk_mul_f32 v[42:43], v[34:35], v[34:35]
	v_cvt_pk_bf16_f32 v32, v36, v37
	v_cvt_pk_bf16_f32 v33, v38, v39
	v_cvt_pk_bf16_f32 v34, v40, v41
	v_cvt_pk_bf16_f32 v35, v42, v43
	global_store_dwordx4 v[50:51], v[32:35], off offset:256
	s_nop 1
	v_fmamk_f32 v32, v163, 0x3a800000, v223
	v_cmp_gt_f32_e32 vcc, s29, v32
	v_mul_f32_e32 v33, 0x4b800000, v32
	v_ashrrev_i32_e32 v163, 31, v162
	v_cndmask_b32_e32 v32, v32, v33, vcc
	v_rsq_f32_e32 v32, v32
	v_lshlrev_b64 v[34:35], 13, v[162:163]
	v_lshl_add_u64 v[34:35], s[90:91], 0, v[34:35]
	v_lshl_add_u64 v[34:35], v[34:35], 0, v[160:161]
	v_mul_f32_e32 v33, 0x45800000, v32
	v_cndmask_b32_e32 v32, v32, v33, vcc
	v_pk_fma_f32 v[24:25], v[24:25], v[32:33], v[120:121] op_sel_hi:[1,0,1]
	v_pk_fma_f32 v[30:31], v[30:31], v[32:33], v[130:131] op_sel_hi:[1,0,1]
	v_pk_fma_f32 v[28:29], v[28:29], v[32:33], v[128:129] op_sel_hi:[1,0,1]
	v_pk_fma_f32 v[26:27], v[26:27], v[32:33], v[122:123] op_sel_hi:[1,0,1]
	v_max_f32_e32 v24, 0, v24
	v_max_f32_e32 v25, 0, v25
	v_max_f32_e32 v28, 0, v28
	v_max_f32_e32 v29, 0, v29
	v_pk_mul_f32 v[36:37], v[24:25], v[24:25]
	v_max_f32_e32 v24, 0, v30
	v_max_f32_e32 v26, 0, v26
	v_max_f32_e32 v25, 0, v31
	v_max_f32_e32 v27, 0, v27
	v_pk_mul_f32 v[28:29], v[28:29], v[28:29]
	v_pk_mul_f32 v[30:31], v[24:25], v[24:25]
	v_pk_mul_f32 v[38:39], v[26:27], v[26:27]
	v_pk_fma_f32 v[16:17], v[16:17], v[32:33], v[108:109] op_sel_hi:[1,0,1]
	v_cvt_pk_bf16_f32 v24, v28, v29
	v_cvt_pk_bf16_f32 v25, v30, v31
	v_cvt_pk_bf16_f32 v26, v36, v37
	v_cvt_pk_bf16_f32 v27, v38, v39
	v_pk_fma_f32 v[22:23], v[22:23], v[32:33], v[114:115] op_sel_hi:[1,0,1]
	v_pk_fma_f32 v[20:21], v[20:21], v[32:33], v[112:113] op_sel_hi:[1,0,1]
	v_pk_fma_f32 v[18:19], v[18:19], v[32:33], v[110:111] op_sel_hi:[1,0,1]
	v_max_f32_e32 v16, 0, v16
	v_max_f32_e32 v17, 0, v17
	global_store_dwordx4 v[34:35], v[24:27], off
	v_max_f32_e32 v20, 0, v20
	v_max_f32_e32 v21, 0, v21
	v_pk_mul_f32 v[24:25], v[16:17], v[16:17]
	v_max_f32_e32 v16, 0, v22
	v_max_f32_e32 v18, 0, v18
	v_max_f32_e32 v17, 0, v23
	v_max_f32_e32 v19, 0, v19
	v_pk_mul_f32 v[20:21], v[20:21], v[20:21]
	v_pk_mul_f32 v[22:23], v[16:17], v[16:17]
	v_pk_mul_f32 v[26:27], v[18:19], v[18:19]
	v_cvt_pk_bf16_f32 v16, v20, v21
	v_cvt_pk_bf16_f32 v17, v22, v23
	v_cvt_pk_bf16_f32 v18, v24, v25
	v_cvt_pk_bf16_f32 v19, v26, v27
	global_store_dwordx4 v[34:35], v[16:19], off offset:256
	s_nop 1
	v_fmamk_f32 v16, v159, 0x3a800000, v223
	v_cmp_gt_f32_e32 vcc, s29, v16
	v_mul_f32_e32 v17, 0x4b800000, v16
	v_ashrrev_i32_e32 v159, 31, v158
	v_cndmask_b32_e32 v16, v16, v17, vcc
	v_rsq_f32_e32 v16, v16
	v_lshlrev_b64 v[18:19], 13, v[158:159]
	v_lshl_add_u64 v[18:19], s[90:91], 0, v[18:19]
	v_lshl_add_u64 v[18:19], v[18:19], 0, v[160:161]
	v_mul_f32_e32 v17, 0x45800000, v16
	v_cndmask_b32_e32 v16, v16, v17, vcc
	v_pk_fma_f32 v[8:9], v[8:9], v[16:17], v[120:121] op_sel_hi:[1,0,1]
	v_pk_fma_f32 v[14:15], v[14:15], v[16:17], v[130:131] op_sel_hi:[1,0,1]
	v_pk_fma_f32 v[12:13], v[12:13], v[16:17], v[128:129] op_sel_hi:[1,0,1]
	v_pk_fma_f32 v[10:11], v[10:11], v[16:17], v[122:123] op_sel_hi:[1,0,1]
	v_max_f32_e32 v8, 0, v8
	v_max_f32_e32 v9, 0, v9
	v_max_f32_e32 v12, 0, v12
	v_max_f32_e32 v13, 0, v13
	v_pk_mul_f32 v[20:21], v[8:9], v[8:9]
	v_max_f32_e32 v8, 0, v14
	v_max_f32_e32 v10, 0, v10
	v_max_f32_e32 v9, 0, v15
	v_max_f32_e32 v11, 0, v11
	v_pk_mul_f32 v[12:13], v[12:13], v[12:13]
	v_pk_mul_f32 v[14:15], v[8:9], v[8:9]
	v_pk_mul_f32 v[22:23], v[10:11], v[10:11]
	v_pk_fma_f32 v[0:1], v[0:1], v[16:17], v[108:109] op_sel_hi:[1,0,1]
	v_cvt_pk_bf16_f32 v8, v12, v13
	v_cvt_pk_bf16_f32 v9, v14, v15
	v_cvt_pk_bf16_f32 v10, v20, v21
	v_cvt_pk_bf16_f32 v11, v22, v23
	v_pk_fma_f32 v[6:7], v[6:7], v[16:17], v[114:115] op_sel_hi:[1,0,1]
	v_pk_fma_f32 v[4:5], v[4:5], v[16:17], v[112:113] op_sel_hi:[1,0,1]
	v_pk_fma_f32 v[2:3], v[2:3], v[16:17], v[110:111] op_sel_hi:[1,0,1]
	v_max_f32_e32 v0, 0, v0
	v_max_f32_e32 v1, 0, v1
	global_store_dwordx4 v[18:19], v[8:11], off
	v_max_f32_e32 v4, 0, v4
	v_max_f32_e32 v5, 0, v5
	v_pk_mul_f32 v[8:9], v[0:1], v[0:1]
	v_max_f32_e32 v0, 0, v6
	v_max_f32_e32 v2, 0, v2
	v_max_f32_e32 v1, 0, v7
	v_max_f32_e32 v3, 0, v3
	v_pk_mul_f32 v[4:5], v[4:5], v[4:5]
	v_pk_mul_f32 v[6:7], v[0:1], v[0:1]
	v_pk_mul_f32 v[10:11], v[2:3], v[2:3]
	v_cvt_pk_bf16_f32 v0, v4, v5
	v_cvt_pk_bf16_f32 v1, v6, v7
	v_cvt_pk_bf16_f32 v2, v8, v9
	v_cvt_pk_bf16_f32 v3, v10, v11
	s_andn2_b64 vcc, exec, s[40:41]
	global_store_dwordx4 v[18:19], v[0:3], off offset:256
	s_cbranch_vccnz .LBB0_846
	s_andn2_b64 vcc, exec, s[12:13]
	s_cbranch_vccnz .LBB0_845
	s_barrier
	s_branch .LBB0_845

.LBB0_870:
	s_ashr_i32 s51, s50, 31
	s_lshl_b64 s[52:53], s[50:51], s70
	s_add_u32 s52, s37, s52
	s_addc_u32 s53, s36, s53
	s_and_b64 s[54:55], s[42:43], exec
	s_cselect_b32 s51, s53, s47
	s_cselect_b32 s60, s52, s46
	s_ashr_i32 s49, s48, 31
	s_lshl_b64 s[54:55], s[48:49], s70
	s_add_u32 s54, s64, s54
	s_addc_u32 s55, s65, s55
	s_and_b64 s[62:63], s[42:43], exec
	s_cselect_b32 s49, s55, s45
	s_cselect_b32 s61, s54, s44
	s_add_u32 s62, s44, 0x100
	s_addc_u32 s63, s45, 0
	s_add_u32 s44, s46, 0x80
	s_addc_u32 s45, s47, 0
	s_mov_b32 s46, 0
	s_add_i32 vcc_lo, s46, 2
	s_add_u32 s20, s44, 0x80
	s_addc_u32 s21, s45, 0
	s_add_i32 s23, 0, 0x10000
	s_cmp_eq_u32 s25, s46
	s_cselect_b32 s47, s51, s21
	s_cselect_b32 s46, s60, s20
	s_cselect_b32 s21, s49, s63
	s_cselect_b32 s20, s61, s62
	s_add_i32 vcc_hi, 0, 0x14000
	v_add_u32_e32 v72, s23, v245
	v_add_u32_e32 v160, vcc_hi, v245
	ds_read_b128 v[60:63], v72
	ds_read_b128 v[64:67], v72 offset:1024
	ds_read_b128 v[68:71], v72 offset:2048
	ds_read_b128 v[72:75], v72 offset:3072
	ds_read_b128 v[148:151], v160
	ds_read_b128 v[152:155], v160 offset:1024
	ds_read_b128 v[156:159], v160 offset:2048
	ds_read_b128 v[160:163], v160 offset:3072
	v_lshl_add_u64 v[210:211], s[44:45], 0, v[192:193]
	s_add_i32 m0, s71, 0xc000
	ds_read_b128 v[164:167], v247
	ds_read_b128 v[168:171], v247 offset:1024
	ds_read_b128 v[172:175], v247 offset:2048
	ds_read_b128 v[176:179], v247 offset:3072
	ds_read_b128 v[194:197], v247 offset:4096
	ds_read_b128 v[198:201], v247 offset:5120
	ds_read_b128 v[202:205], v247 offset:6144
	ds_read_b128 v[206:209], v247 offset:7168
	global_load_lds_dwordx4 v[210:211], off
	v_lshl_add_u64 v[210:211], s[44:45], 0, v[190:191]
	s_add_i32 m0, s71, 0xe000
	s_nop 0
	global_load_lds_dwordx4 v[210:211], off
	s_waitcnt vmcnt(8)
	s_waitcnt lgkmcnt(0)
	s_barrier
	s_setprio 1
	s_waitcnt lgkmcnt(0)
	v_mfma_f32_16x16x32_bf16 v[144:147], v[60:63], v[164:167], 0
	v_mfma_f32_16x16x32_bf16 v[140:143], v[68:71], v[164:167], 0
	v_mfma_f32_16x16x32_bf16 v[128:131], v[60:63], v[172:175], 0
	v_mfma_f32_16x16x32_bf16 v[124:127], v[68:71], v[172:175], 0
	v_mfma_f32_16x16x32_bf16 v[112:115], v[60:63], v[194:197], 0
	v_mfma_f32_16x16x32_bf16 v[108:111], v[68:71], v[194:197], 0
	v_mfma_f32_16x16x32_bf16 v[92:95], v[60:63], v[202:205], 0
	v_mfma_f32_16x16x32_bf16 v[88:91], v[68:71], v[202:205], 0
	v_mfma_f32_16x16x32_bf16 v[144:147], v[64:67], v[168:171], v[144:147]
	v_mfma_f32_16x16x32_bf16 v[140:143], v[72:75], v[168:171], v[140:143]
	v_mfma_f32_16x16x32_bf16 v[128:131], v[64:67], v[176:179], v[128:131]
	v_mfma_f32_16x16x32_bf16 v[124:127], v[72:75], v[176:179], v[124:127]
	v_mfma_f32_16x16x32_bf16 v[112:115], v[64:67], v[198:201], v[112:115]
	v_mfma_f32_16x16x32_bf16 v[108:111], v[72:75], v[198:201], v[108:111]
	v_mfma_f32_16x16x32_bf16 v[92:95], v[64:67], v[206:209], v[92:95]
	v_mfma_f32_16x16x32_bf16 v[88:91], v[72:75], v[206:209], v[88:91]
	s_setprio 0
	s_setprio 1
	v_mfma_f32_16x16x32_bf16 v[136:139], v[148:151], v[164:167], 0
	v_mfma_f32_16x16x32_bf16 v[132:135], v[156:159], v[164:167], 0
	v_mfma_f32_16x16x32_bf16 v[120:123], v[148:151], v[172:175], 0
	v_mfma_f32_16x16x32_bf16 v[116:119], v[156:159], v[172:175], 0
	v_mfma_f32_16x16x32_bf16 v[104:107], v[148:151], v[194:197], 0
	v_mfma_f32_16x16x32_bf16 v[100:103], v[156:159], v[194:197], 0
	v_mfma_f32_16x16x32_bf16 v[84:87], v[148:151], v[202:205], 0
	v_mfma_f32_16x16x32_bf16 v[80:83], v[156:159], v[202:205], 0
	v_mfma_f32_16x16x32_bf16 v[136:139], v[152:155], v[168:171], v[136:139]
	v_mfma_f32_16x16x32_bf16 v[132:135], v[160:163], v[168:171], v[132:135]
	v_mfma_f32_16x16x32_bf16 v[120:123], v[152:155], v[176:179], v[120:123]
	v_mfma_f32_16x16x32_bf16 v[116:119], v[160:163], v[176:179], v[116:119]
	v_mfma_f32_16x16x32_bf16 v[104:107], v[152:155], v[198:201], v[104:107]
	v_mfma_f32_16x16x32_bf16 v[100:103], v[160:163], v[198:201], v[100:103]
	v_mfma_f32_16x16x32_bf16 v[84:87], v[152:155], v[206:209], v[84:87]
	v_mfma_f32_16x16x32_bf16 v[80:83], v[160:163], v[206:209], v[80:83]
	s_setprio 0
	s_barrier
	s_add_i32 s23, s23, s67
	v_lshl_add_u64 v[210:211], s[20:21], 0, v[96:97]
	s_mov_b32 m0, s23
	ds_read_b128 v[164:167], v247 offset:16384
	ds_read_b128 v[168:171], v247 offset:17408
	ds_read_b128 v[172:175], v247 offset:18432
	ds_read_b128 v[176:179], v247 offset:19456
	ds_read_b128 v[194:197], v247 offset:20480
	ds_read_b128 v[198:201], v247 offset:21504
	ds_read_b128 v[202:205], v247 offset:22528
	ds_read_b128 v[206:209], v247 offset:23552
	global_load_lds_dwordx4 v[210:211], off
	s_add_i32 m0, s23, 0x2000
	v_lshl_add_u64 v[212:213], s[20:21], 0, v[188:189]
	s_add_u32 s20, s20, s68
	s_addc_u32 s21, s21, 0
	s_add_i32 s23, vcc_hi, s67
	global_load_lds_dwordx4 v[212:213], off
	v_lshl_add_u64 v[214:215], s[20:21], 0, v[96:97]
	s_mov_b32 m0, s23
	v_lshl_add_u64 v[216:217], s[20:21], 0, v[188:189]
	global_load_lds_dwordx4 v[214:215], off
	s_add_i32 m0, s23, 0x2000
	v_lshl_add_u64 v[218:219], s[46:47], 0, v[96:97]
	global_load_lds_dwordx4 v[216:217], off
	s_mov_b32 m0, s71
	v_lshl_add_u64 v[228:229], s[46:47], 0, v[188:189]
	global_load_lds_dwordx4 v[218:219], off
	s_mov_b32 m0, s92
	s_nop 0
	global_load_lds_dwordx4 v[228:229], off
	s_waitcnt vmcnt(8)
	s_waitcnt lgkmcnt(0)
	s_barrier
	s_setprio 1
	s_waitcnt lgkmcnt(0)
	v_mfma_f32_16x16x32_bf16 v[76:79], v[60:63], v[164:167], 0
	v_mfma_f32_16x16x32_bf16 v[56:59], v[68:71], v[164:167], 0
	v_mfma_f32_16x16x32_bf16 v[44:47], v[60:63], v[172:175], 0
	v_mfma_f32_16x16x32_bf16 v[40:43], v[68:71], v[172:175], 0
	v_mfma_f32_16x16x32_bf16 v[28:31], v[60:63], v[194:197], 0
	v_mfma_f32_16x16x32_bf16 v[24:27], v[68:71], v[194:197], 0
	v_mfma_f32_16x16x32_bf16 v[12:15], v[60:63], v[202:205], 0
	v_mfma_f32_16x16x32_bf16 v[8:11], v[68:71], v[202:205], 0
	v_mfma_f32_16x16x32_bf16 v[76:79], v[64:67], v[168:171], v[76:79]
	v_mfma_f32_16x16x32_bf16 v[56:59], v[72:75], v[168:171], v[56:59]
	v_mfma_f32_16x16x32_bf16 v[44:47], v[64:67], v[176:179], v[44:47]
	v_mfma_f32_16x16x32_bf16 v[40:43], v[72:75], v[176:179], v[40:43]
	v_mfma_f32_16x16x32_bf16 v[28:31], v[64:67], v[198:201], v[28:31]
	v_mfma_f32_16x16x32_bf16 v[24:27], v[72:75], v[198:201], v[24:27]
	v_mfma_f32_16x16x32_bf16 v[12:15], v[64:67], v[206:209], v[12:15]
	v_mfma_f32_16x16x32_bf16 v[8:11], v[72:75], v[206:209], v[8:11]
	s_setprio 0
	s_setprio 1
	v_mfma_f32_16x16x32_bf16 v[52:55], v[148:151], v[164:167], 0
	v_mfma_f32_16x16x32_bf16 v[48:51], v[156:159], v[164:167], 0
	v_mfma_f32_16x16x32_bf16 v[36:39], v[148:151], v[172:175], 0
	v_mfma_f32_16x16x32_bf16 v[32:35], v[156:159], v[172:175], 0
	v_mfma_f32_16x16x32_bf16 v[20:23], v[148:151], v[194:197], 0
	v_mfma_f32_16x16x32_bf16 v[16:19], v[156:159], v[194:197], 0
	v_mfma_f32_16x16x32_bf16 v[4:7], v[148:151], v[202:205], 0
	v_mfma_f32_16x16x32_bf16 v[0:3], v[156:159], v[202:205], 0
	v_mfma_f32_16x16x32_bf16 v[52:55], v[152:155], v[168:171], v[52:55]
	v_mfma_f32_16x16x32_bf16 v[48:51], v[160:163], v[168:171], v[48:51]
	v_mfma_f32_16x16x32_bf16 v[36:39], v[152:155], v[176:179], v[36:39]
	v_mfma_f32_16x16x32_bf16 v[32:35], v[160:163], v[176:179], v[32:35]
	v_mfma_f32_16x16x32_bf16 v[20:23], v[152:155], v[198:201], v[20:23]
	v_mfma_f32_16x16x32_bf16 v[16:19], v[160:163], v[198:201], v[16:19]
	v_mfma_f32_16x16x32_bf16 v[4:7], v[152:155], v[206:209], v[4:7]
	v_mfma_f32_16x16x32_bf16 v[0:3], v[160:163], v[206:209], v[0:3]
	s_setprio 0
	s_barrier
	s_add_i32 s23, 0, 0x18000
	s_add_i32 vcc_hi, 0, 0x1c000
	v_add_u32_e32 v72, s23, v245
	v_add_u32_e32 v160, vcc_hi, v245
	ds_read_b128 v[60:63], v72
	ds_read_b128 v[64:67], v72 offset:1024
	ds_read_b128 v[68:71], v72 offset:2048
	ds_read_b128 v[72:75], v72 offset:3072
	ds_read_b128 v[148:151], v160
	ds_read_b128 v[152:155], v160 offset:1024
	ds_read_b128 v[156:159], v160 offset:2048
	ds_read_b128 v[160:163], v160 offset:3072
	s_add_u32 s20, s46, s68
	s_addc_u32 s21, s47, 0
	s_mov_b32 m0, s93
	v_lshl_add_u64 v[234:235], s[20:21], 0, v[96:97]
	ds_read_b128 v[164:167], v247 offset:32768
	ds_read_b128 v[168:171], v247 offset:33792
	ds_read_b128 v[172:175], v247 offset:34816
	ds_read_b128 v[176:179], v247 offset:35840
	ds_read_b128 v[194:197], v247 offset:36864
	ds_read_b128 v[198:201], v247 offset:37888
	ds_read_b128 v[202:205], v247 offset:38912
	ds_read_b128 v[206:209], v247 offset:39936
	global_load_lds_dwordx4 v[234:235], off
	v_lshl_add_u64 v[234:235], s[20:21], 0, v[188:189]
	s_mov_b32 m0, s94
	s_nop 0
	global_load_lds_dwordx4 v[234:235], off
	s_waitcnt vmcnt(8)
	s_waitcnt lgkmcnt(0)
	s_barrier
	s_setprio 1
	s_waitcnt lgkmcnt(0)
	v_mfma_f32_16x16x32_bf16 v[144:147], v[60:63], v[164:167], v[144:147]
	v_mfma_f32_16x16x32_bf16 v[140:143], v[68:71], v[164:167], v[140:143]
	v_mfma_f32_16x16x32_bf16 v[128:131], v[60:63], v[172:175], v[128:131]
	v_mfma_f32_16x16x32_bf16 v[124:127], v[68:71], v[172:175], v[124:127]
	v_mfma_f32_16x16x32_bf16 v[112:115], v[60:63], v[194:197], v[112:115]
	v_mfma_f32_16x16x32_bf16 v[108:111], v[68:71], v[194:197], v[108:111]
	v_mfma_f32_16x16x32_bf16 v[92:95], v[60:63], v[202:205], v[92:95]
	v_mfma_f32_16x16x32_bf16 v[88:91], v[68:71], v[202:205], v[88:91]
	v_mfma_f32_16x16x32_bf16 v[144:147], v[64:67], v[168:171], v[144:147]
	v_mfma_f32_16x16x32_bf16 v[140:143], v[72:75], v[168:171], v[140:143]
	v_mfma_f32_16x16x32_bf16 v[128:131], v[64:67], v[176:179], v[128:131]
	v_mfma_f32_16x16x32_bf16 v[124:127], v[72:75], v[176:179], v[124:127]
	v_mfma_f32_16x16x32_bf16 v[112:115], v[64:67], v[198:201], v[112:115]
	v_mfma_f32_16x16x32_bf16 v[108:111], v[72:75], v[198:201], v[108:111]
	v_mfma_f32_16x16x32_bf16 v[92:95], v[64:67], v[206:209], v[92:95]
	v_mfma_f32_16x16x32_bf16 v[88:91], v[72:75], v[206:209], v[88:91]
	s_setprio 0
	s_setprio 1
	v_mfma_f32_16x16x32_bf16 v[136:139], v[148:151], v[164:167], v[136:139]
	v_mfma_f32_16x16x32_bf16 v[132:135], v[156:159], v[164:167], v[132:135]
	v_mfma_f32_16x16x32_bf16 v[120:123], v[148:151], v[172:175], v[120:123]
	v_mfma_f32_16x16x32_bf16 v[116:119], v[156:159], v[172:175], v[116:119]
	v_mfma_f32_16x16x32_bf16 v[104:107], v[148:151], v[194:197], v[104:107]
	v_mfma_f32_16x16x32_bf16 v[100:103], v[156:159], v[194:197], v[100:103]
	v_mfma_f32_16x16x32_bf16 v[84:87], v[148:151], v[202:205], v[84:87]
	v_mfma_f32_16x16x32_bf16 v[80:83], v[156:159], v[202:205], v[80:83]
	v_mfma_f32_16x16x32_bf16 v[136:139], v[152:155], v[168:171], v[136:139]
	v_mfma_f32_16x16x32_bf16 v[132:135], v[160:163], v[168:171], v[132:135]
	v_mfma_f32_16x16x32_bf16 v[120:123], v[152:155], v[176:179], v[120:123]
	v_mfma_f32_16x16x32_bf16 v[116:119], v[160:163], v[176:179], v[116:119]
	v_mfma_f32_16x16x32_bf16 v[104:107], v[152:155], v[198:201], v[104:107]
	v_mfma_f32_16x16x32_bf16 v[100:103], v[160:163], v[198:201], v[100:103]
	v_mfma_f32_16x16x32_bf16 v[84:87], v[152:155], v[206:209], v[84:87]
	v_mfma_f32_16x16x32_bf16 v[80:83], v[160:163], v[206:209], v[80:83]
	s_setprio 0
	s_barrier
	s_add_i32 s20, s23, s67
	v_lshl_add_u64 v[210:211], v[210:211], 0, s[30:31]
	s_mov_b32 m0, s20
	ds_read_b128 v[164:167], v247 offset:49152
	ds_read_b128 v[168:171], v247 offset:50176
	ds_read_b128 v[172:175], v247 offset:51200
	ds_read_b128 v[176:179], v247 offset:52224
	ds_read_b128 v[194:197], v247 offset:53248
	ds_read_b128 v[198:201], v247 offset:54272
	ds_read_b128 v[202:205], v247 offset:55296
	ds_read_b128 v[206:209], v247 offset:56320
	global_load_lds_dwordx4 v[210:211], off
	v_lshl_add_u64 v[210:211], v[212:213], 0, s[30:31]
	s_add_i32 m0, s20, 0x2000
	s_add_i32 s20, vcc_hi, s67
	global_load_lds_dwordx4 v[210:211], off
	v_lshl_add_u64 v[210:211], v[214:215], 0, s[30:31]
	s_mov_b32 m0, s20
	s_nop 0
	global_load_lds_dwordx4 v[210:211], off
	v_lshl_add_u64 v[210:211], v[216:217], 0, s[30:31]
	s_add_i32 m0, s20, 0x2000
	s_nop 0
	global_load_lds_dwordx4 v[210:211], off
	v_lshl_add_u64 v[210:211], v[218:219], 0, s[30:31]
	s_mov_b32 m0, s27
	s_nop 0
	global_load_lds_dwordx4 v[210:211], off
	v_lshl_add_u64 v[210:211], v[228:229], 0, s[30:31]
	s_mov_b32 m0, s14
	s_nop 0
	global_load_lds_dwordx4 v[210:211], off
	s_waitcnt vmcnt(8)
	s_waitcnt lgkmcnt(0)
	s_barrier
	s_setprio 1
	s_waitcnt lgkmcnt(0)
	v_mfma_f32_16x16x32_bf16 v[76:79], v[60:63], v[164:167], v[76:79]
	v_mfma_f32_16x16x32_bf16 v[56:59], v[68:71], v[164:167], v[56:59]
	v_mfma_f32_16x16x32_bf16 v[44:47], v[60:63], v[172:175], v[44:47]
	v_mfma_f32_16x16x32_bf16 v[40:43], v[68:71], v[172:175], v[40:43]
	v_mfma_f32_16x16x32_bf16 v[28:31], v[60:63], v[194:197], v[28:31]
	v_mfma_f32_16x16x32_bf16 v[24:27], v[68:71], v[194:197], v[24:27]
	v_mfma_f32_16x16x32_bf16 v[12:15], v[60:63], v[202:205], v[12:15]
	v_mfma_f32_16x16x32_bf16 v[8:11], v[68:71], v[202:205], v[8:11]
	v_mfma_f32_16x16x32_bf16 v[76:79], v[64:67], v[168:171], v[76:79]
	v_mfma_f32_16x16x32_bf16 v[56:59], v[72:75], v[168:171], v[56:59]
	v_mfma_f32_16x16x32_bf16 v[44:47], v[64:67], v[176:179], v[44:47]
	v_mfma_f32_16x16x32_bf16 v[40:43], v[72:75], v[176:179], v[40:43]
	v_mfma_f32_16x16x32_bf16 v[28:31], v[64:67], v[198:201], v[28:31]
	v_mfma_f32_16x16x32_bf16 v[24:27], v[72:75], v[198:201], v[24:27]
	v_mfma_f32_16x16x32_bf16 v[12:15], v[64:67], v[206:209], v[12:15]
	v_mfma_f32_16x16x32_bf16 v[8:11], v[72:75], v[206:209], v[8:11]
	s_setprio 0
	s_setprio 1
	v_mfma_f32_16x16x32_bf16 v[52:55], v[148:151], v[164:167], v[52:55]
	v_mfma_f32_16x16x32_bf16 v[48:51], v[156:159], v[164:167], v[48:51]
	v_mfma_f32_16x16x32_bf16 v[36:39], v[148:151], v[172:175], v[36:39]
	v_mfma_f32_16x16x32_bf16 v[32:35], v[156:159], v[172:175], v[32:35]
	v_mfma_f32_16x16x32_bf16 v[20:23], v[148:151], v[194:197], v[20:23]
	v_mfma_f32_16x16x32_bf16 v[16:19], v[156:159], v[194:197], v[16:19]
	v_mfma_f32_16x16x32_bf16 v[4:7], v[148:151], v[202:205], v[4:7]
	v_mfma_f32_16x16x32_bf16 v[0:3], v[156:159], v[202:205], v[0:3]
	v_mfma_f32_16x16x32_bf16 v[52:55], v[152:155], v[168:171], v[52:55]
	v_mfma_f32_16x16x32_bf16 v[48:51], v[160:163], v[168:171], v[48:51]
	v_mfma_f32_16x16x32_bf16 v[36:39], v[152:155], v[176:179], v[36:39]
	v_mfma_f32_16x16x32_bf16 v[32:35], v[160:163], v[176:179], v[32:35]
	v_mfma_f32_16x16x32_bf16 v[20:23], v[152:155], v[198:201], v[20:23]
	v_mfma_f32_16x16x32_bf16 v[16:19], v[160:163], v[198:201], v[16:19]
	v_mfma_f32_16x16x32_bf16 v[4:7], v[152:155], v[206:209], v[4:7]
	v_mfma_f32_16x16x32_bf16 v[0:3], v[160:163], v[206:209], v[0:3]
	s_setprio 0
	s_barrier
	s_add_u32 s62, s62, 0x100
	s_addc_u32 s63, s63, 0
	s_add_u32 s44, s44, 0x100
	s_addc_u32 s45, s45, 0
	s_cmp_ge_u32 vcc_lo, s24
	s_mov_b32 s46, vcc_lo
	s_cbranch_scc1 .Lpeel_exit_resid

.Lpeel_exit_resid:
	s_and_b64 vcc, exec, s[18:19]
	s_cbranch_vccz .LBB0_874
	s_barrier

.LBB0_1061:
	s_ashr_i32 s13, s12, 31
	s_lshl_b64 s[14:15], s[12:13], 19
	s_add_u32 s14, s88, s14
	s_addc_u32 s15, s89, s15
	s_and_b64 s[16:17], s[44:45], exec
	s_cselect_b32 s13, s15, s47
	s_cselect_b32 s37, s14, s46
	s_ashr_i32 s11, s10, 31
	s_lshl_b64 s[16:17], s[10:11], 19
	s_add_u32 s16, s87, s16
	v_readlane_b32 s11, v255, 24
	s_addc_u32 s17, s11, s17
	s_and_b64 s[26:27], s[44:45], exec
	s_cselect_b32 s11, s17, s19
	s_cselect_b32 s48, s16, s18
	s_add_u32 s49, s18, 0x100
	s_addc_u32 s50, s19, 0
	s_add_u32 s18, s46, 0x40080
	s_addc_u32 s19, s47, 0
	s_mov_b32 s51, -2
	s_waitcnt vmcnt(0)
	s_waitcnt lgkmcnt(0)
	s_add_u32 s20, s18, 0xfffc0080
	s_addc_u32 s21, s19, -1
	s_add_i32 s23, 0, 0x10000
	s_cmp_eq_u32 s51, 12
	s_cselect_b32 s47, s13, s21
	s_cselect_b32 s46, s37, s20
	s_cselect_b32 s27, s11, s50
	s_cselect_b32 s26, s48, s49
	s_add_i32 s20, 0, 0x14000
	v_add_u32_e32 v52, s23, v187
	v_add_u32_e32 v98, s20, v187
	ds_read_b128 v[40:43], v52
	ds_read_b128 v[44:47], v52 offset:1024
	ds_read_b128 v[48:51], v52 offset:2048
	ds_read_b128 v[52:55], v52 offset:3072
	ds_read_b128 v[148:151], v98
	ds_read_b128 v[152:155], v98 offset:1024
	ds_read_b128 v[156:159], v98 offset:2048
	ds_read_b128 v[160:163], v98 offset:3072
	v_lshl_add_u64 v[234:235], s[18:19], 0, v[196:197]
	s_add_i32 m0, s65, 0xc000
	ds_read_b128 v[164:167], v239
	ds_read_b128 v[168:171], v239 offset:1024
	ds_read_b128 v[198:201], v239 offset:2048
	ds_read_b128 v[202:205], v239 offset:3072
	ds_read_b128 v[206:209], v239 offset:4096
	ds_read_b128 v[210:213], v239 offset:5120
	ds_read_b128 v[214:217], v239 offset:6144
	ds_read_b128 v[218:221], v239 offset:7168
	global_load_lds_dwordx4 v[234:235], off
	v_lshl_add_u64 v[234:235], s[18:19], 0, v[194:195]
	s_add_i32 m0, s65, 0xe000
	s_nop 0
	global_load_lds_dwordx4 v[234:235], off
	s_waitcnt vmcnt(8)
	s_waitcnt lgkmcnt(0)
	s_barrier
	s_setprio 1
	s_waitcnt lgkmcnt(0)
	v_mfma_f32_16x16x32_bf16 v[144:147], v[40:43], v[164:167], 0
	v_mfma_f32_16x16x32_bf16 v[124:127], v[48:51], v[164:167], 0
	v_mfma_f32_16x16x32_bf16 v[140:143], v[40:43], v[198:201], 0
	v_mfma_f32_16x16x32_bf16 v[136:139], v[48:51], v[198:201], 0
	v_mfma_f32_16x16x32_bf16 v[120:123], v[40:43], v[206:209], 0
	v_mfma_f32_16x16x32_bf16 v[116:119], v[48:51], v[206:209], 0
	v_mfma_f32_16x16x32_bf16 v[104:107], v[40:43], v[214:217], 0
	v_mfma_f32_16x16x32_bf16 v[100:103], v[48:51], v[214:217], 0
	v_mfma_f32_16x16x32_bf16 v[144:147], v[44:47], v[168:171], v[144:147]
	v_mfma_f32_16x16x32_bf16 v[124:127], v[52:55], v[168:171], v[124:127]
	v_mfma_f32_16x16x32_bf16 v[140:143], v[44:47], v[202:205], v[140:143]
	v_mfma_f32_16x16x32_bf16 v[136:139], v[52:55], v[202:205], v[136:139]
	v_mfma_f32_16x16x32_bf16 v[120:123], v[44:47], v[210:213], v[120:123]
	v_mfma_f32_16x16x32_bf16 v[116:119], v[52:55], v[210:213], v[116:119]
	v_mfma_f32_16x16x32_bf16 v[104:107], v[44:47], v[218:221], v[104:107]
	v_mfma_f32_16x16x32_bf16 v[100:103], v[52:55], v[218:221], v[100:103]
	s_setprio 0
	s_setprio 1
	v_mfma_f32_16x16x32_bf16 v[12:15], v[148:151], v[164:167], 0
	v_mfma_f32_16x16x32_bf16 v[8:11], v[156:159], v[164:167], 0
	v_mfma_f32_16x16x32_bf16 v[132:135], v[148:151], v[198:201], 0
	v_mfma_f32_16x16x32_bf16 v[128:131], v[156:159], v[198:201], 0
	v_mfma_f32_16x16x32_bf16 v[112:115], v[148:151], v[206:209], 0
	v_mfma_f32_16x16x32_bf16 v[108:111], v[156:159], v[206:209], 0
	v_mfma_f32_16x16x32_bf16 v[92:95], v[148:151], v[214:217], 0
	v_mfma_f32_16x16x32_bf16 v[88:91], v[156:159], v[214:217], 0
	v_mfma_f32_16x16x32_bf16 v[12:15], v[152:155], v[168:171], v[12:15]
	v_mfma_f32_16x16x32_bf16 v[8:11], v[160:163], v[168:171], v[8:11]
	v_mfma_f32_16x16x32_bf16 v[132:135], v[152:155], v[202:205], v[132:135]
	v_mfma_f32_16x16x32_bf16 v[128:131], v[160:163], v[202:205], v[128:131]
	v_mfma_f32_16x16x32_bf16 v[112:115], v[152:155], v[210:213], v[112:115]
	v_mfma_f32_16x16x32_bf16 v[108:111], v[160:163], v[210:213], v[108:111]
	v_mfma_f32_16x16x32_bf16 v[92:95], v[152:155], v[218:221], v[92:95]
	v_mfma_f32_16x16x32_bf16 v[88:91], v[160:163], v[218:221], v[88:91]
	s_setprio 0
	s_barrier
	s_add_i32 s21, s23, s64
	v_lshl_add_u64 v[234:235], s[26:27], 0, v[172:173]
	s_mov_b32 m0, s21
	ds_read_b128 v[164:167], v239 offset:16384
	ds_read_b128 v[168:171], v239 offset:17408
	ds_read_b128 v[198:201], v239 offset:18432
	ds_read_b128 v[202:205], v239 offset:19456
	ds_read_b128 v[206:209], v239 offset:20480
	ds_read_b128 v[210:213], v239 offset:21504
	ds_read_b128 v[214:217], v239 offset:22528
	ds_read_b128 v[218:221], v239 offset:23552
	global_load_lds_dwordx4 v[234:235], off
	s_add_i32 m0, s21, 0x2000
	s_add_u32 s52, s26, 0x40000
	v_lshl_add_u64 v[236:237], s[26:27], 0, v[96:97]
	s_addc_u32 s53, s27, 0
	s_add_i32 s20, s20, s64
	global_load_lds_dwordx4 v[236:237], off
	v_lshl_add_u64 v[242:243], s[52:53], 0, v[172:173]
	s_mov_b32 m0, s20
	v_lshl_add_u64 v[244:245], s[46:47], 0, v[96:97]
	global_load_lds_dwordx4 v[242:243], off
	v_lshl_add_u64 v[242:243], s[52:53], 0, v[96:97]
	s_add_i32 m0, s20, 0x2000
	s_nop 0
	global_load_lds_dwordx4 v[242:243], off
	v_lshl_add_u64 v[242:243], s[46:47], 0, v[172:173]
	s_mov_b32 m0, s65
	s_nop 0
	global_load_lds_dwordx4 v[242:243], off
	s_mov_b32 m0, s66
	s_nop 0
	global_load_lds_dwordx4 v[244:245], off
	s_waitcnt vmcnt(8)
	s_waitcnt lgkmcnt(0)
	s_barrier
	s_setprio 1
	s_waitcnt lgkmcnt(0)
	v_mfma_f32_16x16x32_bf16 v[84:87], v[40:43], v[164:167], 0
	v_mfma_f32_16x16x32_bf16 v[80:83], v[48:51], v[164:167], 0
	v_mfma_f32_16x16x32_bf16 v[68:71], v[40:43], v[198:201], 0
	v_mfma_f32_16x16x32_bf16 v[64:67], v[48:51], v[198:201], 0
	v_mfma_f32_16x16x32_bf16 v[36:39], v[40:43], v[206:209], 0
	v_mfma_f32_16x16x32_bf16 v[32:35], v[48:51], v[206:209], 0
	v_mfma_f32_16x16x32_bf16 v[20:23], v[40:43], v[214:217], 0
	v_mfma_f32_16x16x32_bf16 v[16:19], v[48:51], v[214:217], 0
	v_mfma_f32_16x16x32_bf16 v[84:87], v[44:47], v[168:171], v[84:87]
	v_mfma_f32_16x16x32_bf16 v[80:83], v[52:55], v[168:171], v[80:83]
	v_mfma_f32_16x16x32_bf16 v[68:71], v[44:47], v[202:205], v[68:71]
	v_mfma_f32_16x16x32_bf16 v[64:67], v[52:55], v[202:205], v[64:67]
	v_mfma_f32_16x16x32_bf16 v[36:39], v[44:47], v[210:213], v[36:39]
	v_mfma_f32_16x16x32_bf16 v[32:35], v[52:55], v[210:213], v[32:35]
	v_mfma_f32_16x16x32_bf16 v[20:23], v[44:47], v[218:221], v[20:23]
	v_mfma_f32_16x16x32_bf16 v[16:19], v[52:55], v[218:221], v[16:19]
	s_setprio 0
	s_setprio 1
	v_mfma_f32_16x16x32_bf16 v[28:31], v[148:151], v[206:209], 0
	v_mfma_f32_16x16x32_bf16 v[24:27], v[156:159], v[206:209], 0
	v_mfma_f32_16x16x32_bf16 v[4:7], v[148:151], v[214:217], 0
	v_mfma_f32_16x16x32_bf16 v[0:3], v[156:159], v[214:217], 0
	v_mfma_f32_16x16x32_bf16 v[40:43], v[148:151], v[164:167], 0
	v_mfma_f32_16x16x32_bf16 v[44:47], v[156:159], v[164:167], 0
	v_mfma_f32_16x16x32_bf16 v[48:51], v[148:151], v[198:201], 0
	v_mfma_f32_16x16x32_bf16 v[52:55], v[156:159], v[198:201], 0
	v_mfma_f32_16x16x32_bf16 v[28:31], v[152:155], v[210:213], v[28:31]
	v_mfma_f32_16x16x32_bf16 v[24:27], v[160:163], v[210:213], v[24:27]
	v_mfma_f32_16x16x32_bf16 v[4:7], v[152:155], v[218:221], v[4:7]
	v_mfma_f32_16x16x32_bf16 v[0:3], v[160:163], v[218:221], v[0:3]
	v_mfma_f32_16x16x32_bf16 v[40:43], v[152:155], v[168:171], v[40:43]
	v_mfma_f32_16x16x32_bf16 v[44:47], v[160:163], v[168:171], v[44:47]
	v_mfma_f32_16x16x32_bf16 v[48:51], v[152:155], v[202:205], v[48:51]
	v_mfma_f32_16x16x32_bf16 v[52:55], v[160:163], v[202:205], v[52:55]
	s_setprio 0
	s_barrier
	s_add_i32 s20, 0, 0x18000
	s_add_i32 s21, 0, 0x1c000
	v_add_u32_e32 v76, s20, v187
	v_add_u32_e32 v98, s21, v187
	ds_read_b128 v[56:59], v76
	ds_read_b128 v[60:63], v76 offset:1024
	ds_read_b128 v[72:75], v76 offset:2048
	ds_read_b128 v[76:79], v76 offset:3072
	ds_read_b128 v[148:151], v98
	ds_read_b128 v[152:155], v98 offset:1024
	ds_read_b128 v[156:159], v98 offset:2048
	ds_read_b128 v[160:163], v98 offset:3072
	s_add_u32 s46, s46, 0x40000
	s_addc_u32 s47, s47, 0
	s_mov_b32 m0, s67
	v_lshl_add_u64 v[246:247], s[46:47], 0, v[172:173]
	ds_read_b128 v[164:167], v239 offset:32768
	ds_read_b128 v[168:171], v239 offset:33792
	ds_read_b128 v[198:201], v239 offset:34816
	ds_read_b128 v[202:205], v239 offset:35840
	ds_read_b128 v[206:209], v239 offset:36864
	ds_read_b128 v[210:213], v239 offset:37888
	ds_read_b128 v[214:217], v239 offset:38912
	ds_read_b128 v[218:221], v239 offset:39936
	global_load_lds_dwordx4 v[246:247], off
	v_lshl_add_u64 v[246:247], s[46:47], 0, v[96:97]
	s_mov_b32 m0, s70
	s_nop 0
	global_load_lds_dwordx4 v[246:247], off
	s_waitcnt vmcnt(8)
	s_waitcnt lgkmcnt(0)
	s_barrier
	s_setprio 1
	s_waitcnt lgkmcnt(0)
	v_mfma_f32_16x16x32_bf16 v[144:147], v[56:59], v[164:167], v[144:147]
	v_mfma_f32_16x16x32_bf16 v[124:127], v[72:75], v[164:167], v[124:127]
	v_mfma_f32_16x16x32_bf16 v[140:143], v[56:59], v[198:201], v[140:143]
	v_mfma_f32_16x16x32_bf16 v[136:139], v[72:75], v[198:201], v[136:139]
	v_mfma_f32_16x16x32_bf16 v[120:123], v[56:59], v[206:209], v[120:123]
	v_mfma_f32_16x16x32_bf16 v[116:119], v[72:75], v[206:209], v[116:119]
	v_mfma_f32_16x16x32_bf16 v[104:107], v[56:59], v[214:217], v[104:107]
	v_mfma_f32_16x16x32_bf16 v[100:103], v[72:75], v[214:217], v[100:103]
	v_mfma_f32_16x16x32_bf16 v[144:147], v[60:63], v[168:171], v[144:147]
	v_mfma_f32_16x16x32_bf16 v[124:127], v[76:79], v[168:171], v[124:127]
	v_mfma_f32_16x16x32_bf16 v[140:143], v[60:63], v[202:205], v[140:143]
	v_mfma_f32_16x16x32_bf16 v[136:139], v[76:79], v[202:205], v[136:139]
	v_mfma_f32_16x16x32_bf16 v[120:123], v[60:63], v[210:213], v[120:123]
	v_mfma_f32_16x16x32_bf16 v[116:119], v[76:79], v[210:213], v[116:119]
	v_mfma_f32_16x16x32_bf16 v[104:107], v[60:63], v[218:221], v[104:107]
	v_mfma_f32_16x16x32_bf16 v[100:103], v[76:79], v[218:221], v[100:103]
	s_setprio 0
	s_setprio 1
	v_mfma_f32_16x16x32_bf16 v[12:15], v[148:151], v[164:167], v[12:15]
	v_mfma_f32_16x16x32_bf16 v[8:11], v[156:159], v[164:167], v[8:11]
	v_mfma_f32_16x16x32_bf16 v[132:135], v[148:151], v[198:201], v[132:135]
	v_mfma_f32_16x16x32_bf16 v[128:131], v[156:159], v[198:201], v[128:131]
	v_mfma_f32_16x16x32_bf16 v[112:115], v[148:151], v[206:209], v[112:115]
	v_mfma_f32_16x16x32_bf16 v[108:111], v[156:159], v[206:209], v[108:111]
	v_mfma_f32_16x16x32_bf16 v[92:95], v[148:151], v[214:217], v[92:95]
	v_mfma_f32_16x16x32_bf16 v[88:91], v[156:159], v[214:217], v[88:91]
	v_mfma_f32_16x16x32_bf16 v[12:15], v[152:155], v[168:171], v[12:15]
	v_mfma_f32_16x16x32_bf16 v[8:11], v[160:163], v[168:171], v[8:11]
	v_mfma_f32_16x16x32_bf16 v[132:135], v[152:155], v[202:205], v[132:135]
	v_mfma_f32_16x16x32_bf16 v[128:131], v[160:163], v[202:205], v[128:131]
	v_mfma_f32_16x16x32_bf16 v[112:115], v[152:155], v[210:213], v[112:115]
	v_mfma_f32_16x16x32_bf16 v[108:111], v[160:163], v[210:213], v[108:111]
	v_mfma_f32_16x16x32_bf16 v[92:95], v[152:155], v[218:221], v[92:95]
	v_mfma_f32_16x16x32_bf16 v[88:91], v[160:163], v[218:221], v[88:91]
	s_setprio 0
	s_barrier
	s_add_i32 s20, s20, s64
	v_lshl_add_u64 v[234:235], v[234:235], 0, s[30:31]
	s_mov_b32 m0, s20
	ds_read_b128 v[164:167], v239 offset:49152
	ds_read_b128 v[168:171], v239 offset:50176
	ds_read_b128 v[198:201], v239 offset:51200
	ds_read_b128 v[202:205], v239 offset:52224
	ds_read_b128 v[206:209], v239 offset:53248
	ds_read_b128 v[210:213], v239 offset:54272
	ds_read_b128 v[214:217], v239 offset:55296
	ds_read_b128 v[218:221], v239 offset:56320
	global_load_lds_dwordx4 v[234:235], off
	s_add_i32 m0, s20, 0x2000
	s_add_u32 s26, s26, 0x40080
	v_lshl_add_u64 v[234:235], v[236:237], 0, s[30:31]
	s_addc_u32 s27, s27, 0
	s_add_i32 s20, s21, s64
	global_load_lds_dwordx4 v[234:235], off
	v_lshl_add_u64 v[234:235], s[26:27], 0, v[172:173]
	s_mov_b32 m0, s20
	s_nop 0
	global_load_lds_dwordx4 v[234:235], off
	v_lshl_add_u64 v[234:235], s[26:27], 0, v[96:97]
	s_add_i32 m0, s20, 0x2000
	s_nop 0
	global_load_lds_dwordx4 v[234:235], off
	v_lshl_add_u64 v[234:235], v[242:243], 0, s[30:31]
	s_mov_b32 m0, s93
	s_nop 0
	global_load_lds_dwordx4 v[234:235], off
	v_lshl_add_u64 v[234:235], v[244:245], 0, s[30:31]
	s_mov_b32 m0, s94
	s_nop 0
	global_load_lds_dwordx4 v[234:235], off
	s_waitcnt vmcnt(8)
	s_waitcnt lgkmcnt(0)
	s_barrier
	s_setprio 1
	s_waitcnt lgkmcnt(0)
	v_mfma_f32_16x16x32_bf16 v[84:87], v[56:59], v[164:167], v[84:87]
	v_mfma_f32_16x16x32_bf16 v[80:83], v[72:75], v[164:167], v[80:83]
	v_mfma_f32_16x16x32_bf16 v[68:71], v[56:59], v[198:201], v[68:71]
	v_mfma_f32_16x16x32_bf16 v[64:67], v[72:75], v[198:201], v[64:67]
	v_mfma_f32_16x16x32_bf16 v[36:39], v[56:59], v[206:209], v[36:39]
	v_mfma_f32_16x16x32_bf16 v[32:35], v[72:75], v[206:209], v[32:35]
	v_mfma_f32_16x16x32_bf16 v[20:23], v[56:59], v[214:217], v[20:23]
	v_mfma_f32_16x16x32_bf16 v[16:19], v[72:75], v[214:217], v[16:19]
	v_mfma_f32_16x16x32_bf16 v[84:87], v[60:63], v[168:171], v[84:87]
	v_mfma_f32_16x16x32_bf16 v[80:83], v[76:79], v[168:171], v[80:83]
	v_mfma_f32_16x16x32_bf16 v[68:71], v[60:63], v[202:205], v[68:71]
	v_mfma_f32_16x16x32_bf16 v[64:67], v[76:79], v[202:205], v[64:67]
	v_mfma_f32_16x16x32_bf16 v[36:39], v[60:63], v[210:213], v[36:39]
	v_mfma_f32_16x16x32_bf16 v[32:35], v[76:79], v[210:213], v[32:35]
	v_mfma_f32_16x16x32_bf16 v[20:23], v[60:63], v[218:221], v[20:23]
	v_mfma_f32_16x16x32_bf16 v[16:19], v[76:79], v[218:221], v[16:19]
	s_setprio 0
	s_setprio 1
	v_mfma_f32_16x16x32_bf16 v[40:43], v[148:151], v[164:167], v[40:43]
	v_mfma_f32_16x16x32_bf16 v[76:79], v[152:155], v[168:171], v[40:43]
	v_mfma_f32_16x16x32_bf16 v[40:43], v[156:159], v[164:167], v[44:47]
	v_mfma_f32_16x16x32_bf16 v[72:75], v[160:163], v[168:171], v[40:43]
	v_mfma_f32_16x16x32_bf16 v[40:43], v[148:151], v[198:201], v[48:51]
	v_mfma_f32_16x16x32_bf16 v[60:63], v[152:155], v[202:205], v[40:43]
	v_mfma_f32_16x16x32_bf16 v[40:43], v[156:159], v[198:201], v[52:55]
	v_mfma_f32_16x16x32_bf16 v[28:31], v[148:151], v[206:209], v[28:31]
	v_mfma_f32_16x16x32_bf16 v[24:27], v[156:159], v[206:209], v[24:27]
	v_mfma_f32_16x16x32_bf16 v[4:7], v[148:151], v[214:217], v[4:7]
	v_mfma_f32_16x16x32_bf16 v[0:3], v[156:159], v[214:217], v[0:3]
	v_mfma_f32_16x16x32_bf16 v[56:59], v[160:163], v[202:205], v[40:43]
	v_mfma_f32_16x16x32_bf16 v[28:31], v[152:155], v[210:213], v[28:31]
	v_mfma_f32_16x16x32_bf16 v[24:27], v[160:163], v[210:213], v[24:27]
	v_mfma_f32_16x16x32_bf16 v[4:7], v[152:155], v[218:221], v[4:7]
	v_mfma_f32_16x16x32_bf16 v[0:3], v[160:163], v[218:221], v[0:3]
	s_setprio 0
	s_barrier
	s_add_i32 s51, s51, 2
	s_add_u32 s49, s49, 0x100
	s_addc_u32 s50, s50, 0
	s_add_u32 s18, s18, 0x100
	s_addc_u32 s19, s19, 0
	s_cmp_gt_u32 s51, 13
	s_cbranch_scc1 .Lpeel_exit_inproj

.Lpeel_exit_inproj:
	s_and_b64 vcc, exec, s[6:7]
	s_cbranch_vccz .LBB0_1065
	s_barrier

.Lwc_l0:
	s_movk_i32 s99, 0x1420
	s_movk_i32 s98, 0x2c3f
	s_branch .Lwc_go
.Lwc_l1:
	s_movk_i32 s99, 0x2a40
	s_movk_i32 s98, 0x425f
	s_branch .Lwc_go
.Lwc_l2:
	s_movk_i32 s99, 0x4060
	s_movk_i32 s98, 0x587f

.LBB0_1210:
	s_movk_i32 s98, 0x161f
	s_mov_b32 s99, 0
	s_movk_i32 s0, 0x2400
	v_readfirstlane_b32 s17, v186
	s_mov_b32 s16, s3
	v_cmp_gt_i32_e32 vcc, s0, v186
	s_and_saveexec_b64 s[6:7], vcc
	s_cbranch_execz .LBB0_1222
	v_max_i32_e32 v0, 0x2200, v186
	v_sub_u32_e32 v0, v0, v186
	s_waitcnt lgkmcnt(0)
	v_add_u32_e32 v1, 0x1ff, v0
	s_movk_i32 s0, 0x1ff
	v_cmp_lt_u32_e32 vcc, s0, v1
	s_mov_b64 s[0:1], -1
	v_mov_b32_e32 v0, v186
	s_and_saveexec_b64 s[8:9], vcc
	s_cbranch_execz .LBB0_1219
	v_lshrrev_b32_e32 v2, 9, v1
	v_add_u32_e32 v187, 0x200, v186
	v_add_u32_e32 v3, -1, v2
	v_cmp_lt_u32_e32 vcc, 1, v3
	v_mov_b32_e32 v4, 0
	v_mov_b64_e32 v[0:1], v[186:187]
	s_and_saveexec_b64 s[10:11], vcc
	s_cbranch_execz .LBB0_1216
	v_lshrrev_b32_e32 v0, 1, v3
	v_add_u32_e32 v0, 1, v0
	v_readlane_b32 s40, v252, 21
	v_and_b32_e32 v4, -2, v0
	v_lshl_add_u32 v5, v186, 2, 0
	s_mov_b32 s14, 0
	s_mov_b64 s[12:13], 0
	v_mov_b64_e32 v[0:1], v[186:187]
	v_readlane_b32 s42, v252, 23
	v_readlane_b32 s43, v252, 24
	v_readlane_b32 s46, v252, 27
	v_readlane_b32 s47, v252, 28
	s_movk_i32 s15, 0x2000
	s_mov_b32 s20, 0xbfb8aa3b
	s_mov_b32 s21, 0x42ce8ed0
	s_mov_b32 s24, 0xc2b17218
	v_readlane_b32 s41, v252, 22
	v_readlane_b32 s44, v252, 25
	v_readlane_b32 s45, v252, 26
	v_readlane_b32 s48, v252, 29
	v_readlane_b32 s49, v252, 30
	v_readlane_b32 s50, v252, 31
	v_readlane_b32 s51, v252, 32
	v_readlane_b32 s52, v252, 33
	v_readlane_b32 s53, v252, 34
	v_readlane_b32 s54, v252, 35
	v_readlane_b32 s55, v252, 36

.Lwc_entry:
	s_ashr_i32 s0, s17, 6
	v_readlane_b32 s6, v254, 31
	s_add_i32 s12, s0, s6
	s_add_i32 s12, s12, s99
	s_cmp_gt_i32 s12, s98
	v_readlane_b32 s7, v254, 32
	s_cbranch_scc1 .LBB0_1350
	v_lshlrev_b32_e32 v1, 3, v186
	s_lshl_b32 s0, s0, 14
	v_bfe_u32 v0, v186, 5, 1
	v_bfe_u32 v41, v186, 3, 3
	v_and_b32_e32 v2, 56, v1
	s_add_i32 s1, s0, 0
	v_mul_u32_u24_e32 v1, 0x84, v2
	v_lshlrev_b32_e32 v3, 2, v41
	v_mul_u32_u24_e32 v84, 0x84, v0
	v_lshlrev_b32_e32 v36, 2, v40
	v_add3_u32 v80, s1, v1, v3
	v_or_b32_e32 v1, 2, v0
	v_or_b32_e32 v3, 6, v0
	v_or_b32_e32 v4, 4, v0
	v_or_b32_e32 v5, 10, v0
	v_or_b32_e32 v6, 8, v0
	v_or_b32_e32 v7, 14, v0
	v_or_b32_e32 v8, 12, v0
	v_or_b32_e32 v9, 18, v0
	v_or_b32_e32 v10, 16, v0
	v_or_b32_e32 v11, 22, v0
	v_or_b32_e32 v12, 20, v0
	v_or_b32_e32 v13, 26, v0
	v_or_b32_e32 v14, 24, v0
	v_or_b32_e32 v15, 30, v0
	v_or_b32_e32 v16, 28, v0
	v_or_b32_e32 v17, 34, v0
	v_or_b32_e32 v18, 32, v0
	v_or_b32_e32 v19, 38, v0
	v_or_b32_e32 v20, 36, v0
	v_or_b32_e32 v21, 42, v0
	v_or_b32_e32 v22, 40, v0
	v_or_b32_e32 v23, 46, v0
	v_or_b32_e32 v24, 44, v0
	v_or_b32_e32 v25, 50, v0
	v_or_b32_e32 v26, 48, v0
	v_or_b32_e32 v27, 54, v0
	v_or_b32_e32 v28, 52, v0
	v_or_b32_e32 v29, 58, v0
	v_or_b32_e32 v30, 56, v0
	v_or_b32_e32 v31, 62, v0
	v_or_b32_e32 v32, 60, v0
	v_or_b32_e32 v34, s0, v84
	v_mov_b32_e32 v37, v99
	v_lshlrev_b32_e32 v38, 2, v0
	v_mov_b32_e32 v39, v99
	s_lshl_b32 s13, s16, 3
	v_add_u32_e32 v33, s1, v36
	v_or_b32_e32 v81, 8, v41
	v_or_b32_e32 v82, 16, v41
	v_or_b32_e32 v83, 24, v41
	v_mul_u32_u24_e32 v85, 0x84, v1
	v_mul_u32_u24_e32 v86, 0x84, v4
	v_mul_u32_u24_e32 v87, 0x84, v3
	v_mul_u32_u24_e32 v88, 0x84, v6
	v_mul_u32_u24_e32 v89, 0x84, v5
	v_mul_u32_u24_e32 v90, 0x84, v8
	v_mul_u32_u24_e32 v91, 0x84, v7
	v_mul_u32_u24_e32 v92, 0x84, v10
	v_mul_u32_u24_e32 v93, 0x84, v9
	v_mul_u32_u24_e32 v94, 0x84, v12
	v_mul_u32_u24_e32 v95, 0x84, v11
	v_mul_u32_u24_e32 v96, 0x84, v14
	v_mul_u32_u24_e32 v97, 0x84, v13
	v_mul_u32_u24_e32 v100, 0x84, v16
	v_mul_u32_u24_e32 v101, 0x84, v15
	v_mul_u32_u24_e32 v102, 0x84, v18
	v_mul_u32_u24_e32 v103, 0x84, v17
	v_mul_u32_u24_e32 v104, 0x84, v20
	v_mul_u32_u24_e32 v105, 0x84, v19
	v_mul_u32_u24_e32 v106, 0x84, v22
	v_mul_u32_u24_e32 v107, 0x84, v21
	v_mul_u32_u24_e32 v108, 0x84, v24
	v_mul_u32_u24_e32 v109, 0x84, v23
	v_mul_u32_u24_e32 v110, 0x84, v26
	v_mul_u32_u24_e32 v111, 0x84, v25
	v_mul_u32_u24_e32 v112, 0x84, v28
	v_mul_u32_u24_e32 v113, 0x84, v27
	v_mul_u32_u24_e32 v114, 0x84, v30
	v_mul_u32_u24_e32 v115, 0x84, v29
	v_mul_u32_u24_e32 v116, 0x84, v32
	v_mul_u32_u24_e32 v117, 0x84, v31
	v_add3_u32 v118, v34, v36, 0
	v_lshl_add_u64 v[34:35], s[84:85], 0, v[36:37]
	v_lshl_add_u64 v[36:37], s[80:81], 0, v[36:37]
	v_lshl_add_u64 v[38:39], s[78:79], 0, v[38:39]
	s_branch .LBB0_1262
.LBB0_1261:
	s_add_i32 s12, s12, s13
	s_cmp_gt_i32 s12, s98
	s_cbranch_scc1 .LBB0_1350
